# plus down2 gather address chain trimmed to 1 VALU with SGPR-base addressing, and XCD-aware out-projection tile order
# speedup vs baseline: 1.0196x; 1.0029x over previous
;     ...
;   for (int tile = t_start; tile < t_total; tile += t_step) {
;     int mt, nt;
;     if (cntS) { mt = tile / cntS; nt = xi + 8 * (tile % cntS); } else { mt = tile / Ntiles; nt = tile % Ntiles; }
;     const int m0 = mt * 128, n0 = nt * 128;
.LBB0_479:
	s_cmp_lg_u32 s26, 0x200
	s_cbranch_scc1 .Lmy_xr_plain_op0
	s_and_b32 s6, s43, 7
	s_bfe_u32 s7, s43, 0x60003
	s_lshr_b32 s15, s43, 9
	s_lshl_b32 s15, s15, 6
	s_add_i32 s7, s7, s15
	s_lshr_b32 s15, s7, 3
	s_lshl_b32 s15, s15, 3
	s_and_b32 s7, s7, 7
	s_add_i32 s15, s15, s6
	s_mov_b32 s6, s7
	s_mov_b32 s7, s15
	s_branch .Lmy_xr_join_op0

; DI int opaque_tid() { int t = threadIdx.x; asm volatile("" : "+v"(t)); return t; }
; DI void gemm_mainloop(const bf16* __restrict__ A, int lda, const bf16* __restrict__ Bt, int ldb, int K, int m0, int n0,
;                       bf16* As, bf16* Bs, f32x16& acc0, f32x16& acc1, f32x16& acc2, f32x16& acc3) {
;   const int tid = opaque_tid(), lane = tid & 63, w = tid >> 6, r = lane & 31, g = lane >> 5;
;   const int lrow = tid >> 3, lcc = (tid & 7) * 8;
;   const bf16* ap = A + (size_t)(m0 + lrow) * lda + lcc;
;   const bf16* bp = Bt + (size_t)(n0 + lrow) * ldb + lcc;
;   GTile t0, t1;
;   asm volatile("" ::: "memory");
;   const int nkt = K >> 6;
;   int kb = ((((m0 >> 7) * 5 + (n0 >> 7) * 3) >> 1) % nkt) << 6;
;     ...
;   gt_load(t0, ap, bp, lda, ldb, KW(0));
;   gt_load(t1, ap, bp, lda, ldb, KW(64));
; #pragma unroll
;   for (int i = 0; i < 16; ++i) { acc0[i] = 0.f; acc1[i] = 0.f; acc2[i] = 0.f; acc3[i] = 0.f; }
;   bf16* asw = As + lrow * LDT + lcc;
;   bf16* bsw = Bs + lrow * LDT + lcc;
;   const bf16* asr = As + (32 * w + r) * LDT + g * 8;
;   const bf16* bsr = Bs + r * LDT + g * 8;
.Lmy_xr_join_op0:
	s_lshl_b32 s15, s7, 7
	s_lshl_b32 s14, s6, 7
	v_mov_b32_e32 v8, v160
	s_mul_i32 s7, s7, 5
	s_mul_i32 s6, s6, 3
	s_add_i32 s6, s6, s7
	v_ashrrev_i32_e32 v9, 3, v8
	v_add_u32_e32 v0, s15, v9
	s_ashr_i32 s7, s6, 1
	s_ashr_i32 s6, s6, 31
	v_ashrrev_i32_e32 v1, 31, v0
	s_lshr_b32 s6, s6, 28
	v_lshlrev_b64 v[0:1], 11, v[0:1]
	v_lshlrev_b32_e32 v2, 4, v8
	s_add_i32 s6, s7, s6
	v_lshl_add_u64 v[0:1], s[36:37], 0, v[0:1]
	v_and_b32_e32 v128, 0x70, v2
	s_and_b32 s6, s6, -16
	v_lshl_add_u64 v[132:133], v[0:1], 0, v[128:129]
	v_add_u32_e32 v0, s14, v9
	s_sub_i32 s30, s7, s6
	v_ashrrev_i32_e32 v1, 31, v0
	s_lshl_b32 s28, s30, 6
	v_lshlrev_b64 v[0:1], 11, v[0:1]
	s_ashr_i32 s29, s28, 31
	v_lshl_add_u64 v[0:1], s[12:13], 0, v[0:1]
	s_lshl_b64 s[6:7], s[28:29], 1
	v_lshl_add_u64 v[134:135], v[0:1], 0, v[128:129]
	v_lshl_add_u64 v[0:1], v[132:133], 0, s[6:7]
	v_add_co_u32_e32 v4, vcc, s4, v0
	v_lshl_add_u64 v[2:3], v[134:135], 0, s[6:7]
	s_nop 0
	v_addc_co_u32_e32 v5, vcc, 0, v1, vcc
	v_add_co_u32_e32 v6, vcc, s5, v0
	s_cmp_lt_i32 s30, 15
	s_nop 0
	v_addc_co_u32_e32 v7, vcc, 0, v1, vcc
	global_load_dwordx4 v[64:67], v[4:5], off
	global_load_dwordx4 v[68:71], v[6:7], off
	v_add_co_u32_e32 v4, vcc, s40, v0
	global_load_dwordx4 v[72:75], v[0:1], off
	global_load_dwordx4 v[76:79], v[2:3], off
	v_addc_co_u32_e32 v5, vcc, 0, v1, vcc
	v_add_co_u32_e32 v6, vcc, s4, v2
	s_cselect_b32 s7, 0, -1
	s_nop 0
	v_addc_co_u32_e32 v7, vcc, 0, v3, vcc
	global_load_dwordx4 v[80:83], v[4:5], off
	global_load_dwordx4 v[84:87], v[6:7], off
	v_add_co_u32_e32 v4, vcc, s5, v2
	s_cselect_b32 s6, 0, 0xfffff800
	s_nop 0
	v_addc_co_u32_e32 v5, vcc, 0, v3, vcc
	v_add_co_u32_e32 v6, vcc, s40, v2
	v_lshl_add_u64 v[0:1], v[0:1], 0, s[6:7]
	s_nop 0
	v_addc_co_u32_e32 v7, vcc, 0, v3, vcc
	global_load_dwordx4 v[96:99], v[4:5], off
	global_load_dwordx4 v[104:107], v[6:7], off
	v_add_co_u32_e32 v4, vcc, s4, v0
	v_lshl_add_u64 v[2:3], v[2:3], 0, s[6:7]
	s_nop 0
	v_addc_co_u32_e32 v5, vcc, 0, v1, vcc
	v_add_co_u32_e32 v6, vcc, s5, v0
	v_mad_u64_u32 v[136:137], s[6:7], v9, s41, v[128:129]
	s_nop 0
	v_addc_co_u32_e32 v7, vcc, 0, v1, vcc
	global_load_dwordx4 v[88:91], v[4:5], off offset:128
	global_load_dwordx4 v[92:95], v[6:7], off offset:128
	v_add_co_u32_e32 v4, vcc, s40, v0
	global_load_dwordx4 v[100:103], v[0:1], off offset:128
	global_load_dwordx4 v[108:111], v[2:3], off offset:128
	v_addc_co_u32_e32 v5, vcc, 0, v1, vcc
	v_add_co_u32_e32 v0, vcc, s4, v2
	s_sub_i32 s44, 0x400, s28
	s_nop 0
	v_addc_co_u32_e32 v1, vcc, 0, v3, vcc
	global_load_dwordx4 v[112:115], v[4:5], off offset:128
	global_load_dwordx4 v[116:119], v[0:1], off offset:128
	v_add_co_u32_e32 v0, vcc, s5, v2
	s_sub_i32 s45, 0x340, s28
	s_nop 0
	v_addc_co_u32_e32 v1, vcc, 0, v3, vcc
	v_add_co_u32_e32 v2, vcc, s40, v2
	s_mov_b64 s[30:31], 0
	s_nop 0
	v_addc_co_u32_e32 v3, vcc, 0, v3, vcc
	global_load_dwordx4 v[120:123], v[0:1], off offset:128
	global_load_dwordx4 v[124:127], v[2:3], off offset:128
	v_and_b32_e32 v1, 31, v8
	v_lshrrev_b32_e32 v0, 1, v8
	v_and_or_b32 v2, v0, s42, v1
	v_and_b32_e32 v0, 16, v0
	v_mad_u64_u32 v[138:139], s[6:7], v2, s41, v[0:1]
	v_mad_u32_u24 v128, v1, s41, v0
	v_mov_b32_e32 v0, 0
	v_mov_b32_e32 v1, v129
	v_mov_b32_e32 v2, v129
	v_mov_b32_e32 v3, v129
	v_mov_b32_e32 v4, v129
	v_mov_b32_e32 v5, v129
	v_mov_b32_e32 v6, v129
	v_mov_b32_e32 v7, v129
	v_mov_b32_e32 v8, v129
	v_mov_b32_e32 v9, v129
	v_mov_b32_e32 v10, v129
	v_mov_b32_e32 v11, v129
	v_mov_b32_e32 v12, v129
	v_mov_b32_e32 v13, v129
	v_mov_b32_e32 v14, v129
	v_mov_b32_e32 v15, v129
	v_mov_b32_e32 v16, 0
	v_mov_b32_e32 v17, v129
	v_mov_b32_e32 v18, v129
	v_mov_b32_e32 v19, v129
	v_mov_b32_e32 v20, v129
	v_mov_b32_e32 v21, v129
	v_mov_b32_e32 v22, v129
	v_mov_b32_e32 v23, v129
	v_mov_b32_e32 v24, v129
	v_mov_b32_e32 v25, v129
	v_mov_b32_e32 v26, v129
	v_mov_b32_e32 v27, v129
	v_mov_b32_e32 v28, v129
	v_mov_b32_e32 v29, v129
	v_mov_b32_e32 v30, v129
	v_mov_b32_e32 v31, v129
	v_mov_b32_e32 v32, 0
	v_mov_b32_e32 v33, v129
	v_mov_b32_e32 v34, v129
	v_mov_b32_e32 v35, v129
	v_mov_b32_e32 v36, v129
	v_mov_b32_e32 v37, v129
	v_mov_b32_e32 v38, v129
	v_mov_b32_e32 v39, v129
	v_mov_b32_e32 v40, v129
	v_mov_b32_e32 v41, v129
	v_mov_b32_e32 v42, v129
	v_mov_b32_e32 v43, v129
	v_mov_b32_e32 v44, v129
	v_mov_b32_e32 v45, v129
	v_mov_b32_e32 v46, v129
	v_mov_b32_e32 v47, v129
	v_mov_b32_e32 v48, 0
	v_mov_b32_e32 v49, v129
	v_mov_b32_e32 v50, v129
	v_mov_b32_e32 v51, v129
	v_mov_b32_e32 v52, v129
	v_mov_b32_e32 v53, v129
	v_mov_b32_e32 v54, v129
	v_mov_b32_e32 v55, v129
	v_mov_b32_e32 v56, v129
	v_mov_b32_e32 v57, v129
	v_mov_b32_e32 v58, v129
	v_mov_b32_e32 v59, v129
	v_mov_b32_e32 v60, v129
	v_mov_b32_e32 v61, v129
	v_mov_b32_e32 v62, v129
	v_mov_b32_e32 v63, v129
	s_branch .LBB0_481

; DI void dn2_issue(u32x4 (&W)[16], const int* pl, const unsigned char* wbase, int grp) {
; #pragma unroll
;   for (int j = 0; j < 16; ++j) W[j] = *(const u32x4*)(wbase + (size_t)pl[8 * j + grp] * 1024);
; DI void peer_down2_phase(const Params& p, unsigned char* smem, int layer, const bf16* __restrict__ x1b, u32* ctr) {
;     ...
;       const int t0 = item * 64 + 16 * w;
;       const unsigned char* wbase = wd + slice * 128 + c * 16;
.LBB0_680:
	s_add_i32 s6, s50, s4
	s_and_b32 s28, s6, 7
	s_and_b64 s[6:7], s[38:39], exec
	s_cselect_b32 s6, s28, s31
	s_lshl_b32 s7, s28, 2
	s_add_u32 s44, s5, s7
	s_addc_u32 s45, s30, 0
	s_lshl_b32 s28, s6, 7
	s_ashr_i32 s29, s28, 31
	s_ashr_i32 s7, s6, 31
	v_lshl_add_u64 v[190:191], v[148:149], 0, s[28:29]
	s_nop 0
	v_readfirstlane_b32 s98, v190
	v_readfirstlane_b32 s99, v191
	v_and_b32_e32 v250, 7, v160
	v_lshlrev_b32_e32 v250, 4, v250
	s_lshl_b64 s[28:29], s[28:29], 1
	s_lshl_b64 s[6:7], s[6:7], 23
	v_lshl_add_u64 v[192:193], v[150:151], 0, s[28:29]
	v_lshl_add_u64 v[194:195], v[152:153], 0, s[28:29]
	v_lshl_add_u64 v[196:197], v[154:155], 0, s[6:7]
	v_mov_b32_e32 v2, v0
	s_branch .LBB0_683

; DI float bflo(u32 u) { return __uint_as_float(u << 16); }
; DI float bfhi(u32 u) { return __uint_as_float(u & 0xffff0000u); }
; DI void dn2_issue(u32x4 (&W)[16], const int* pl, const unsigned char* wbase, int grp) {
; #pragma unroll
;   for (int j = 0; j < 16; ++j) W[j] = *(const u32x4*)(wbase + (size_t)pl[8 * j + grp] * 1024);
; }
; DI void dn2_math(const u32x4 (&W)[16], u32x4 x0, u32x4 x1, float* __restrict__ parow, int lane) {
;   f2 xf[8];
; #pragma unroll
;   for (int q = 0; q < 4; ++q) { xf[q] = f2{bflo(x0[q]), bfhi(x0[q])}; xf[4 + q] = f2{bflo(x1[q]), bfhi(x1[q])}; }
;   float pv[16];
; #pragma unroll
;   for (int j = 0; j < 16; ++j) {
;     f2 s2 = {0.f, 0.f};
; #pragma unroll
;     for (int d = 0; d < 4; ++d) {
;       f2 lo = __builtin_amdgcn_cvt_pk_f32_fp8((int)W[j][d], false);
;       f2 hi = __builtin_amdgcn_cvt_pk_f32_fp8((int)W[j][d], true);
;       s2 = lo * xf[2 * d] + s2;
;       s2 = hi * xf[2 * d + 1] + s2;
;     }
;     pv[j] = s2.x + s2.y;
;   }
; DI void peer_down2_phase(const Params& p, unsigned char* smem, int layer, const bf16* __restrict__ x1b, u32* ctr) {
;     ...
;       for (int tl = 0; tl < 16; tl += 2) {
;         dn2_issue(WB, pl + (tl + 1) * 128, wbase, grp);
;         xb_0 = *(const u32x4*)(xb0 + (size_t)(tl + 1) * 1024); xb_1 = *(const u32x4*)(xb0 + (size_t)(tl + 1) * 1024 + 8);
;         __builtin_amdgcn_sched_barrier(0);
;         dn2_math(WA, xa0, xa1, pbase + (size_t)tl * 128, lane);
.LBB0_694:
	ds_read2_b32 v[134:135], v165 offset1:8
	ds_read2_b32 v[126:127], v165 offset0:16 offset1:24
	ds_read2_b32 v[118:119], v165 offset0:32 offset1:40
	ds_read2_b32 v[110:111], v165 offset0:48 offset1:56
	ds_read2_b32 v[102:103], v165 offset0:64 offset1:72
	ds_read2_b32 v[94:95], v165 offset0:80 offset1:88
	ds_read2_b32 v[86:87], v165 offset0:96 offset1:104
	ds_read2_b32 v[78:79], v165 offset0:112 offset1:120
	s_waitcnt lgkmcnt(7)
	v_lshl_add_u32 v130, v135, 10, v250
	v_lshl_add_u32 v134, v134, 10, v250
	global_load_dwordx4 v[134:137], v134, s[98:99]
	global_load_dwordx4 v[130:133], v130, s[98:99]
	s_waitcnt lgkmcnt(6)
	v_lshl_add_u32 v122, v127, 10, v250
	v_lshl_add_u32 v126, v126, 10, v250
	global_load_dwordx4 v[126:129], v126, s[98:99]
	global_load_dwordx4 v[122:125], v122, s[98:99]
	s_waitcnt lgkmcnt(5)
	v_lshl_add_u32 v114, v119, 10, v250
	v_lshl_add_u32 v118, v118, 10, v250
	global_load_dwordx4 v[118:121], v118, s[98:99]
	global_load_dwordx4 v[114:117], v114, s[98:99]
	s_waitcnt lgkmcnt(4)
	v_lshl_add_u32 v106, v111, 10, v250
	v_lshl_add_u32 v110, v110, 10, v250
	global_load_dwordx4 v[110:113], v110, s[98:99]
	global_load_dwordx4 v[106:109], v106, s[98:99]
	s_waitcnt lgkmcnt(3)
	v_lshl_add_u32 v98, v103, 10, v250
	v_lshl_add_u32 v102, v102, 10, v250
	global_load_dwordx4 v[102:105], v102, s[98:99]
	global_load_dwordx4 v[98:101], v98, s[98:99]
	s_waitcnt lgkmcnt(2)
	v_lshl_add_u32 v90, v95, 10, v250
	v_lshl_add_u32 v94, v94, 10, v250
	global_load_dwordx4 v[94:97], v94, s[98:99]
	global_load_dwordx4 v[90:93], v90, s[98:99]
	s_waitcnt lgkmcnt(1)
	v_lshl_add_u32 v82, v87, 10, v250
	v_lshl_add_u32 v86, v86, 10, v250
	global_load_dwordx4 v[86:89], v86, s[98:99]
	global_load_dwordx4 v[82:85], v82, s[98:99]
	s_waitcnt lgkmcnt(0)
	v_lshl_add_u32 v74, v79, 10, v250
	v_lshl_add_u32 v78, v78, 10, v250
	global_load_dwordx4 v[78:81], v78, s[98:99]
	global_load_dwordx4 v[74:77], v74, s[98:99]
	s_nop 0
	global_load_dwordx4 v[138:141], v[198:199], off offset:-2032
	global_load_dwordx4 v[142:145], v[198:199], off offset:-2048
	s_waitcnt vmcnt(35)
	v_cvt_pk_f32_fp8_e32 v[230:231], v2
	v_cvt_pk_f32_fp8_sdwa v[232:233], v2 src0_sel:WORD_1
	v_cvt_pk_f32_fp8_e32 v[234:235], v3
	s_waitcnt vmcnt(18)
	v_lshlrev_b32_e32 v210, 16, v70
	v_and_b32_e32 v211, 0xffff0000, v70
	v_cvt_pk_f32_fp8_sdwa v[236:237], v3 src0_sel:WORD_1
	v_lshlrev_b32_e32 v212, 16, v71
	v_and_b32_e32 v213, 0xffff0000, v71
	v_pk_fma_f32 v[230:231], v[230:231], v[210:211], 0 op_sel_hi:[1,1,0]
	v_lshlrev_b32_e32 v214, 16, v72
	v_and_b32_e32 v215, 0xffff0000, v72
	v_pk_fma_f32 v[230:231], v[232:233], v[212:213], v[230:231]
	v_cvt_pk_f32_fp8_e32 v[232:233], v4
	v_lshlrev_b32_e32 v216, 16, v73
	v_and_b32_e32 v217, 0xffff0000, v73
	v_pk_fma_f32 v[230:231], v[234:235], v[214:215], v[230:231]
	v_cvt_pk_f32_fp8_sdwa v[234:235], v4 src0_sel:WORD_1
	v_pk_fma_f32 v[230:231], v[236:237], v[216:217], v[230:231]
	v_cvt_pk_f32_fp8_e32 v[236:237], v5
	v_lshlrev_b32_e32 v202, 16, v66
	v_and_b32_e32 v203, 0xffff0000, v66
	v_cvt_pk_f32_fp8_sdwa v[238:239], v5 src0_sel:WORD_1
	v_lshlrev_b32_e32 v204, 16, v67
	v_and_b32_e32 v205, 0xffff0000, v67
	v_pk_fma_f32 v[230:231], v[232:233], v[202:203], v[230:231]
	v_lshlrev_b32_e32 v206, 16, v68
	v_and_b32_e32 v207, 0xffff0000, v68
	v_pk_fma_f32 v[230:231], v[234:235], v[204:205], v[230:231]
	v_lshlrev_b32_e32 v208, 16, v69
	v_and_b32_e32 v209, 0xffff0000, v69
	v_pk_fma_f32 v[230:231], v[236:237], v[206:207], v[230:231]
	v_cvt_pk_f32_fp8_sdwa v[232:233], v6 src0_sel:WORD_1
	v_pk_fma_f32 v[230:231], v[238:239], v[208:209], v[230:231]
	v_cvt_pk_f32_fp8_e32 v[234:235], v7
	v_add_f32_e32 v167, v230, v231
	v_cvt_pk_f32_fp8_e32 v[230:231], v6
	v_cvt_pk_f32_fp8_sdwa v[236:237], v7 src0_sel:WORD_1
	v_cvt_pk_f32_fp8_sdwa v[238:239], v9 src0_sel:WORD_1
	v_pk_fma_f32 v[230:231], v[230:231], v[210:211], 0 op_sel_hi:[1,1,0]
	s_nop 0
	v_pk_fma_f32 v[230:231], v[232:233], v[212:213], v[230:231]
	v_cvt_pk_f32_fp8_e32 v[232:233], v8
	v_pk_fma_f32 v[230:231], v[234:235], v[214:215], v[230:231]
	v_cvt_pk_f32_fp8_sdwa v[234:235], v8 src0_sel:WORD_1
	v_pk_fma_f32 v[230:231], v[236:237], v[216:217], v[230:231]
	v_cvt_pk_f32_fp8_e32 v[236:237], v9
	v_pk_fma_f32 v[230:231], v[232:233], v[202:203], v[230:231]
	v_cvt_pk_f32_fp8_sdwa v[232:233], v10 src0_sel:WORD_1
	v_pk_fma_f32 v[230:231], v[234:235], v[204:205], v[230:231]
	v_cvt_pk_f32_fp8_e32 v[234:235], v11
	v_pk_fma_f32 v[230:231], v[236:237], v[206:207], v[230:231]
	v_cvt_pk_f32_fp8_sdwa v[236:237], v11 src0_sel:WORD_1
	v_pk_fma_f32 v[230:231], v[238:239], v[208:209], v[230:231]
	v_cvt_pk_f32_fp8_sdwa v[238:239], v13 src0_sel:WORD_1
	v_add_f32_e32 v169, v230, v231
	v_cvt_pk_f32_fp8_e32 v[230:231], v10
	v_pk_fma_f32 v[230:231], v[230:231], v[210:211], 0 op_sel_hi:[1,1,0]
	s_nop 0
	v_pk_fma_f32 v[230:231], v[232:233], v[212:213], v[230:231]
	v_cvt_pk_f32_fp8_e32 v[232:233], v12
	v_pk_fma_f32 v[230:231], v[234:235], v[214:215], v[230:231]
	v_cvt_pk_f32_fp8_sdwa v[234:235], v12 src0_sel:WORD_1
	v_pk_fma_f32 v[230:231], v[236:237], v[216:217], v[230:231]
	v_cvt_pk_f32_fp8_e32 v[236:237], v13
	v_pk_fma_f32 v[230:231], v[232:233], v[202:203], v[230:231]
	v_cvt_pk_f32_fp8_sdwa v[232:233], v14 src0_sel:WORD_1
	v_pk_fma_f32 v[230:231], v[234:235], v[204:205], v[230:231]
	v_cvt_pk_f32_fp8_e32 v[234:235], v15
	v_pk_fma_f32 v[230:231], v[236:237], v[206:207], v[230:231]
	v_cvt_pk_f32_fp8_sdwa v[236:237], v15 src0_sel:WORD_1
	v_pk_fma_f32 v[230:231], v[238:239], v[208:209], v[230:231]
	v_cvt_pk_f32_fp8_sdwa v[238:239], v17 src0_sel:WORD_1
	v_add_f32_e32 v171, v230, v231
	v_cvt_pk_f32_fp8_e32 v[230:231], v14
	v_pk_fma_f32 v[230:231], v[230:231], v[210:211], 0 op_sel_hi:[1,1,0]
; DI float bflo(u32 u) { return __uint_as_float(u << 16); }
; DI float bfhi(u32 u) { return __uint_as_float(u & 0xffff0000u); }
; DI void dn2_math(const u32x4 (&W)[16], u32x4 x0, u32x4 x1, float* __restrict__ parow, int lane) {
;   f2 xf[8];
; #pragma unroll
;   for (int q = 0; q < 4; ++q) { xf[q] = f2{bflo(x0[q]), bfhi(x0[q])}; xf[4 + q] = f2{bflo(x1[q]), bfhi(x1[q])}; }
;   float pv[16];
; #pragma unroll
;   for (int j = 0; j < 16; ++j) {
;     f2 s2 = {0.f, 0.f};
; #pragma unroll
;     for (int d = 0; d < 4; ++d) {
;       f2 lo = __builtin_amdgcn_cvt_pk_f32_fp8((int)W[j][d], false);
;       f2 hi = __builtin_amdgcn_cvt_pk_f32_fp8((int)W[j][d], true);
;       s2 = lo * xf[2 * d] + s2;
;       s2 = hi * xf[2 * d + 1] + s2;
;     }
;     pv[j] = s2.x + s2.y;
;   }
	s_nop 0
	v_pk_fma_f32 v[230:231], v[232:233], v[212:213], v[230:231]
	v_cvt_pk_f32_fp8_e32 v[232:233], v16
	v_pk_fma_f32 v[230:231], v[234:235], v[214:215], v[230:231]
	v_cvt_pk_f32_fp8_sdwa v[234:235], v16 src0_sel:WORD_1
	v_pk_fma_f32 v[230:231], v[236:237], v[216:217], v[230:231]
	v_cvt_pk_f32_fp8_e32 v[236:237], v17
	v_pk_fma_f32 v[230:231], v[232:233], v[202:203], v[230:231]
	v_cvt_pk_f32_fp8_sdwa v[232:233], v18 src0_sel:WORD_1
	v_pk_fma_f32 v[230:231], v[234:235], v[204:205], v[230:231]
	v_cvt_pk_f32_fp8_e32 v[234:235], v19
	v_pk_fma_f32 v[230:231], v[236:237], v[206:207], v[230:231]
	v_cvt_pk_f32_fp8_sdwa v[236:237], v19 src0_sel:WORD_1
	v_pk_fma_f32 v[230:231], v[238:239], v[208:209], v[230:231]
	v_cvt_pk_f32_fp8_sdwa v[238:239], v21 src0_sel:WORD_1
	v_add_f32_e32 v173, v230, v231
	v_cvt_pk_f32_fp8_e32 v[230:231], v18
	v_pk_fma_f32 v[230:231], v[230:231], v[210:211], 0 op_sel_hi:[1,1,0]
	s_nop 0
	v_pk_fma_f32 v[230:231], v[232:233], v[212:213], v[230:231]
	v_cvt_pk_f32_fp8_e32 v[232:233], v20
	v_pk_fma_f32 v[230:231], v[234:235], v[214:215], v[230:231]
	v_cvt_pk_f32_fp8_sdwa v[234:235], v20 src0_sel:WORD_1
	v_pk_fma_f32 v[230:231], v[236:237], v[216:217], v[230:231]
	v_cvt_pk_f32_fp8_e32 v[236:237], v21
	v_pk_fma_f32 v[230:231], v[232:233], v[202:203], v[230:231]
	v_cvt_pk_f32_fp8_sdwa v[232:233], v22 src0_sel:WORD_1
	v_pk_fma_f32 v[230:231], v[234:235], v[204:205], v[230:231]
	v_cvt_pk_f32_fp8_e32 v[234:235], v23
	v_pk_fma_f32 v[230:231], v[236:237], v[206:207], v[230:231]
	v_cvt_pk_f32_fp8_sdwa v[236:237], v23 src0_sel:WORD_1
	v_pk_fma_f32 v[230:231], v[238:239], v[208:209], v[230:231]
	v_cvt_pk_f32_fp8_sdwa v[238:239], v25 src0_sel:WORD_1
	v_add_f32_e32 v175, v230, v231
	v_cvt_pk_f32_fp8_e32 v[230:231], v22
	v_pk_fma_f32 v[230:231], v[230:231], v[210:211], 0 op_sel_hi:[1,1,0]
	s_nop 0
	v_pk_fma_f32 v[230:231], v[232:233], v[212:213], v[230:231]
	v_cvt_pk_f32_fp8_e32 v[232:233], v24
	v_pk_fma_f32 v[230:231], v[234:235], v[214:215], v[230:231]
	v_cvt_pk_f32_fp8_sdwa v[234:235], v24 src0_sel:WORD_1
	v_pk_fma_f32 v[230:231], v[236:237], v[216:217], v[230:231]
	v_cvt_pk_f32_fp8_e32 v[236:237], v25
	v_pk_fma_f32 v[230:231], v[232:233], v[202:203], v[230:231]
	v_cvt_pk_f32_fp8_sdwa v[232:233], v26 src0_sel:WORD_1
	v_pk_fma_f32 v[230:231], v[234:235], v[204:205], v[230:231]
	v_cvt_pk_f32_fp8_e32 v[234:235], v27
	v_pk_fma_f32 v[230:231], v[236:237], v[206:207], v[230:231]
	v_cvt_pk_f32_fp8_sdwa v[236:237], v27 src0_sel:WORD_1
	v_pk_fma_f32 v[230:231], v[238:239], v[208:209], v[230:231]
	v_cvt_pk_f32_fp8_sdwa v[238:239], v29 src0_sel:WORD_1
	v_add_f32_e32 v177, v230, v231
	v_cvt_pk_f32_fp8_e32 v[230:231], v26
	v_pk_fma_f32 v[230:231], v[230:231], v[210:211], 0 op_sel_hi:[1,1,0]
	s_nop 0
	v_pk_fma_f32 v[230:231], v[232:233], v[212:213], v[230:231]
	v_cvt_pk_f32_fp8_e32 v[232:233], v28
	v_pk_fma_f32 v[230:231], v[234:235], v[214:215], v[230:231]
	v_cvt_pk_f32_fp8_sdwa v[234:235], v28 src0_sel:WORD_1
	v_pk_fma_f32 v[230:231], v[236:237], v[216:217], v[230:231]
	v_cvt_pk_f32_fp8_e32 v[236:237], v29
	v_pk_fma_f32 v[230:231], v[232:233], v[202:203], v[230:231]
	v_cvt_pk_f32_fp8_sdwa v[232:233], v30 src0_sel:WORD_1
	v_pk_fma_f32 v[230:231], v[234:235], v[204:205], v[230:231]
	v_cvt_pk_f32_fp8_e32 v[234:235], v31
	v_pk_fma_f32 v[230:231], v[236:237], v[206:207], v[230:231]
	v_cvt_pk_f32_fp8_sdwa v[236:237], v31 src0_sel:WORD_1
	v_pk_fma_f32 v[230:231], v[238:239], v[208:209], v[230:231]
	v_cvt_pk_f32_fp8_sdwa v[238:239], v33 src0_sel:WORD_1
	v_add_f32_e32 v179, v230, v231
	v_cvt_pk_f32_fp8_e32 v[230:231], v30
	v_pk_fma_f32 v[230:231], v[230:231], v[210:211], 0 op_sel_hi:[1,1,0]
	s_nop 0
	v_pk_fma_f32 v[230:231], v[232:233], v[212:213], v[230:231]
	v_cvt_pk_f32_fp8_e32 v[232:233], v32
	v_pk_fma_f32 v[230:231], v[234:235], v[214:215], v[230:231]
	v_cvt_pk_f32_fp8_sdwa v[234:235], v32 src0_sel:WORD_1
	v_pk_fma_f32 v[230:231], v[236:237], v[216:217], v[230:231]
	v_cvt_pk_f32_fp8_e32 v[236:237], v33
	v_pk_fma_f32 v[230:231], v[232:233], v[202:203], v[230:231]
	v_cvt_pk_f32_fp8_sdwa v[232:233], v34 src0_sel:WORD_1
	v_pk_fma_f32 v[230:231], v[234:235], v[204:205], v[230:231]
	v_cvt_pk_f32_fp8_e32 v[234:235], v35
	v_pk_fma_f32 v[230:231], v[236:237], v[206:207], v[230:231]
	v_cvt_pk_f32_fp8_sdwa v[236:237], v35 src0_sel:WORD_1
	v_pk_fma_f32 v[230:231], v[238:239], v[208:209], v[230:231]
	v_cvt_pk_f32_fp8_sdwa v[238:239], v37 src0_sel:WORD_1
	v_add_f32_e32 v181, v230, v231
	v_cvt_pk_f32_fp8_e32 v[230:231], v34
	v_pk_fma_f32 v[230:231], v[230:231], v[210:211], 0 op_sel_hi:[1,1,0]
	s_nop 0
	v_pk_fma_f32 v[230:231], v[232:233], v[212:213], v[230:231]
	v_cvt_pk_f32_fp8_e32 v[232:233], v36
	v_pk_fma_f32 v[230:231], v[234:235], v[214:215], v[230:231]
	v_cvt_pk_f32_fp8_sdwa v[234:235], v36 src0_sel:WORD_1
	v_pk_fma_f32 v[230:231], v[236:237], v[216:217], v[230:231]
	v_cvt_pk_f32_fp8_e32 v[236:237], v37
	v_pk_fma_f32 v[230:231], v[232:233], v[202:203], v[230:231]
	v_cvt_pk_f32_fp8_sdwa v[232:233], v38 src0_sel:WORD_1
	v_pk_fma_f32 v[230:231], v[234:235], v[204:205], v[230:231]
	v_cvt_pk_f32_fp8_e32 v[234:235], v39
	v_pk_fma_f32 v[230:231], v[236:237], v[206:207], v[230:231]
	v_cvt_pk_f32_fp8_sdwa v[236:237], v39 src0_sel:WORD_1
	v_pk_fma_f32 v[230:231], v[238:239], v[208:209], v[230:231]
	v_cvt_pk_f32_fp8_sdwa v[238:239], v41 src0_sel:WORD_1
	v_add_f32_e32 v183, v230, v231
	v_cvt_pk_f32_fp8_e32 v[230:231], v38
	v_pk_fma_f32 v[230:231], v[230:231], v[210:211], 0 op_sel_hi:[1,1,0]
	s_nop 0
	v_pk_fma_f32 v[230:231], v[232:233], v[212:213], v[230:231]
	v_cvt_pk_f32_fp8_e32 v[232:233], v40
	v_pk_fma_f32 v[230:231], v[234:235], v[214:215], v[230:231]
; DI void dn2_math(const u32x4 (&W)[16], u32x4 x0, u32x4 x1, float* __restrict__ parow, int lane) {
;     ...
; #pragma unroll
;   for (int j = 0; j < 16; ++j) {
;     f2 s2 = {0.f, 0.f};
; #pragma unroll
;     for (int d = 0; d < 4; ++d) {
;       f2 lo = __builtin_amdgcn_cvt_pk_f32_fp8((int)W[j][d], false);
;       f2 hi = __builtin_amdgcn_cvt_pk_f32_fp8((int)W[j][d], true);
;       s2 = lo * xf[2 * d] + s2;
;       s2 = hi * xf[2 * d + 1] + s2;
;     }
;     pv[j] = s2.x + s2.y;
;   }
;   const bool b2 = lane & 4, b1 = lane & 2, b0 = lane & 1;
;   float q8[8];
; #pragma unroll
;   for (int i = 0; i < 8; ++i) { float snd = b2 ? pv[i] : pv[i + 8]; float kp = b2 ? pv[i + 8] : pv[i]; q8[i] = kp + __shfl_xor(snd, 4); }
	v_cvt_pk_f32_fp8_sdwa v[234:235], v40 src0_sel:WORD_1
	v_pk_fma_f32 v[230:231], v[236:237], v[216:217], v[230:231]
	v_cvt_pk_f32_fp8_e32 v[236:237], v41
	v_pk_fma_f32 v[230:231], v[232:233], v[202:203], v[230:231]
	v_cvt_pk_f32_fp8_sdwa v[232:233], v42 src0_sel:WORD_1
	v_pk_fma_f32 v[230:231], v[234:235], v[204:205], v[230:231]
	v_cvt_pk_f32_fp8_e32 v[234:235], v43
	v_pk_fma_f32 v[230:231], v[236:237], v[206:207], v[230:231]
	v_cvt_pk_f32_fp8_sdwa v[236:237], v43 src0_sel:WORD_1
	v_pk_fma_f32 v[230:231], v[238:239], v[208:209], v[230:231]
	v_cvt_pk_f32_fp8_sdwa v[238:239], v45 src0_sel:WORD_1
	v_add_f32_e32 v185, v230, v231
	v_cvt_pk_f32_fp8_e32 v[230:231], v42
	v_pk_fma_f32 v[230:231], v[230:231], v[210:211], 0 op_sel_hi:[1,1,0]
	s_nop 0
	v_pk_fma_f32 v[230:231], v[232:233], v[212:213], v[230:231]
	v_cvt_pk_f32_fp8_e32 v[232:233], v44
	v_pk_fma_f32 v[230:231], v[234:235], v[214:215], v[230:231]
	v_cvt_pk_f32_fp8_sdwa v[234:235], v44 src0_sel:WORD_1
	v_pk_fma_f32 v[230:231], v[236:237], v[216:217], v[230:231]
	v_cvt_pk_f32_fp8_e32 v[236:237], v45
	v_pk_fma_f32 v[230:231], v[232:233], v[202:203], v[230:231]
	v_cvt_pk_f32_fp8_sdwa v[232:233], v46 src0_sel:WORD_1
	v_pk_fma_f32 v[230:231], v[234:235], v[204:205], v[230:231]
	v_cvt_pk_f32_fp8_e32 v[234:235], v47
	v_pk_fma_f32 v[230:231], v[236:237], v[206:207], v[230:231]
	v_cvt_pk_f32_fp8_sdwa v[236:237], v47 src0_sel:WORD_1
	v_pk_fma_f32 v[230:231], v[238:239], v[208:209], v[230:231]
	v_cvt_pk_f32_fp8_sdwa v[238:239], v49 src0_sel:WORD_1
	v_add_f32_e32 v187, v230, v231
	v_cvt_pk_f32_fp8_e32 v[230:231], v46
	v_pk_fma_f32 v[230:231], v[230:231], v[210:211], 0 op_sel_hi:[1,1,0]
	s_nop 0
	v_pk_fma_f32 v[230:231], v[232:233], v[212:213], v[230:231]
	v_cvt_pk_f32_fp8_e32 v[232:233], v48
	v_pk_fma_f32 v[230:231], v[234:235], v[214:215], v[230:231]
	v_cvt_pk_f32_fp8_sdwa v[234:235], v48 src0_sel:WORD_1
	v_pk_fma_f32 v[230:231], v[236:237], v[216:217], v[230:231]
	v_cvt_pk_f32_fp8_e32 v[236:237], v49
	v_pk_fma_f32 v[230:231], v[232:233], v[202:203], v[230:231]
	v_cvt_pk_f32_fp8_sdwa v[232:233], v50 src0_sel:WORD_1
	v_pk_fma_f32 v[230:231], v[234:235], v[204:205], v[230:231]
	v_cvt_pk_f32_fp8_e32 v[234:235], v51
	v_pk_fma_f32 v[230:231], v[236:237], v[206:207], v[230:231]
	v_cvt_pk_f32_fp8_sdwa v[236:237], v51 src0_sel:WORD_1
	v_pk_fma_f32 v[230:231], v[238:239], v[208:209], v[230:231]
	v_cvt_pk_f32_fp8_sdwa v[238:239], v53 src0_sel:WORD_1
	v_add_f32_e32 v189, v230, v231
	v_cvt_pk_f32_fp8_e32 v[230:231], v50
	v_pk_fma_f32 v[230:231], v[230:231], v[210:211], 0 op_sel_hi:[1,1,0]
	s_nop 0
	v_pk_fma_f32 v[230:231], v[232:233], v[212:213], v[230:231]
	v_cvt_pk_f32_fp8_e32 v[232:233], v52
	v_pk_fma_f32 v[230:231], v[234:235], v[214:215], v[230:231]
	v_cvt_pk_f32_fp8_sdwa v[234:235], v52 src0_sel:WORD_1
	v_pk_fma_f32 v[230:231], v[236:237], v[216:217], v[230:231]
	v_cvt_pk_f32_fp8_e32 v[236:237], v53
	v_pk_fma_f32 v[230:231], v[232:233], v[202:203], v[230:231]
	v_cvt_pk_f32_fp8_sdwa v[232:233], v54 src0_sel:WORD_1
	v_pk_fma_f32 v[230:231], v[234:235], v[204:205], v[230:231]
	v_cvt_pk_f32_fp8_e32 v[234:235], v55
	v_pk_fma_f32 v[230:231], v[236:237], v[206:207], v[230:231]
	v_cvt_pk_f32_fp8_sdwa v[236:237], v55 src0_sel:WORD_1
	v_pk_fma_f32 v[230:231], v[238:239], v[208:209], v[230:231]
	v_cvt_pk_f32_fp8_sdwa v[238:239], v57 src0_sel:WORD_1
	v_add_f32_e32 v240, v230, v231
	v_cvt_pk_f32_fp8_e32 v[230:231], v54
	v_pk_fma_f32 v[230:231], v[230:231], v[210:211], 0 op_sel_hi:[1,1,0]
	s_nop 0
	v_pk_fma_f32 v[230:231], v[232:233], v[212:213], v[230:231]
	v_cvt_pk_f32_fp8_e32 v[232:233], v56
	v_pk_fma_f32 v[230:231], v[234:235], v[214:215], v[230:231]
	v_cvt_pk_f32_fp8_sdwa v[234:235], v56 src0_sel:WORD_1
	v_pk_fma_f32 v[230:231], v[236:237], v[216:217], v[230:231]
	v_cvt_pk_f32_fp8_e32 v[236:237], v57
	v_pk_fma_f32 v[230:231], v[232:233], v[202:203], v[230:231]
	v_cvt_pk_f32_fp8_sdwa v[232:233], v58 src0_sel:WORD_1
	v_pk_fma_f32 v[230:231], v[234:235], v[204:205], v[230:231]
	v_cvt_pk_f32_fp8_e32 v[234:235], v59
	v_pk_fma_f32 v[230:231], v[236:237], v[206:207], v[230:231]
	v_cvt_pk_f32_fp8_sdwa v[236:237], v59 src0_sel:WORD_1
	v_pk_fma_f32 v[230:231], v[238:239], v[208:209], v[230:231]
	v_cvt_pk_f32_fp8_sdwa v[238:239], v61 src0_sel:WORD_1
	v_add_f32_e32 v241, v230, v231
	v_cvt_pk_f32_fp8_e32 v[230:231], v58
	v_pk_fma_f32 v[230:231], v[230:231], v[210:211], 0 op_sel_hi:[1,1,0]
	s_nop 0
	v_pk_fma_f32 v[230:231], v[232:233], v[212:213], v[230:231]
	v_cvt_pk_f32_fp8_e32 v[232:233], v60
	v_pk_fma_f32 v[230:231], v[234:235], v[214:215], v[230:231]
	v_cvt_pk_f32_fp8_sdwa v[234:235], v60 src0_sel:WORD_1
	v_pk_fma_f32 v[230:231], v[236:237], v[216:217], v[230:231]
	v_cvt_pk_f32_fp8_e32 v[236:237], v61
	v_pk_fma_f32 v[230:231], v[232:233], v[202:203], v[230:231]
	v_cvt_pk_f32_fp8_sdwa v[232:233], v62 src0_sel:WORD_1
	v_pk_fma_f32 v[230:231], v[234:235], v[204:205], v[230:231]
	v_cvt_pk_f32_fp8_e32 v[234:235], v63
	v_pk_fma_f32 v[230:231], v[236:237], v[206:207], v[230:231]
	v_cvt_pk_f32_fp8_sdwa v[236:237], v63 src0_sel:WORD_1
	v_pk_fma_f32 v[230:231], v[238:239], v[208:209], v[230:231]
	s_nop 0
	v_add_f32_e32 v238, v230, v231
	v_cvt_pk_f32_fp8_e32 v[230:231], v62
	v_pk_fma_f32 v[210:211], v[230:231], v[210:211], 0 op_sel_hi:[1,1,0]
	s_nop 0
	v_pk_fma_f32 v[210:211], v[232:233], v[212:213], v[210:211]
	v_cvt_pk_f32_fp8_e32 v[212:213], v64
	v_pk_fma_f32 v[210:211], v[234:235], v[214:215], v[210:211]
	v_cvt_pk_f32_fp8_sdwa v[214:215], v64 src0_sel:WORD_1
	v_pk_fma_f32 v[210:211], v[236:237], v[216:217], v[210:211]
	v_cvt_pk_f32_fp8_e32 v[216:217], v65
	v_cvt_pk_f32_fp8_sdwa v[230:231], v65 src0_sel:WORD_1
	v_pk_fma_f32 v[202:203], v[212:213], v[202:203], v[210:211]
	s_nop 0
	v_pk_fma_f32 v[202:203], v[214:215], v[204:205], v[202:203]
	v_cndmask_b32_e64 v204, v171, v187, s[10:11]
	v_pk_fma_f32 v[202:203], v[216:217], v[206:207], v[202:203]
	v_cndmask_b32_e64 v171, v187, v171, s[10:11]
	v_pk_fma_f32 v[202:203], v[230:231], v[208:209], v[202:203]
	v_cndmask_b32_e64 v187, v177, v241, s[10:11]
	v_add_f32_e32 v202, v202, v203
	v_cndmask_b32_e64 v203, v167, v183, s[10:11]
	v_cndmask_b32_e64 v167, v183, v167, s[10:11]
	ds_bpermute_b32 v183, v157, v203
	v_cndmask_b32_e64 v203, v169, v185, s[10:11]
	v_cndmask_b32_e64 v169, v185, v169, s[10:11]
	v_cndmask_b32_e64 v185, v175, v240, s[10:11]
	ds_bpermute_b32 v185, v157, v185
	s_waitcnt lgkmcnt(1)
; DI void dn2_math(const u32x4 (&W)[16], u32x4 x0, u32x4 x1, float* __restrict__ parow, int lane) {
;     ...
;   const bool b2 = lane & 4, b1 = lane & 2, b0 = lane & 1;
;   float q8[8];
; #pragma unroll
;   for (int i = 0; i < 8; ++i) { float snd = b2 ? pv[i] : pv[i + 8]; float kp = b2 ? pv[i + 8] : pv[i]; q8[i] = kp + __shfl_xor(snd, 4); }
;   float q4[4];
; #pragma unroll
;   for (int i = 0; i < 4; ++i) { float snd = b1 ? q8[i] : q8[i + 4]; float kp = b1 ? q8[i + 4] : q8[i]; q4[i] = kp + __shfl_xor(snd, 2); }
;   float r2[2];
; #pragma unroll
;   for (int i = 0; i < 2; ++i) { float snd = b0 ? q4[i] : q4[i + 2]; float kp = b0 ? q4[i + 2] : q4[i]; r2[i] = kp + __shfl_xor(snd, 1); }
;   const int j0 = (b0 ? 2 : 0) + (b1 ? 4 : 0) + (b2 ? 8 : 0);
;   const int grp = lane >> 3;
;   parow[8 * j0 + grp] = r2[0];
;   parow[8 * (j0 + 1) + grp] = r2[1];
; }
; DI void peer_down2_phase(const Params& p, unsigned char* smem, int layer, const bf16* __restrict__ x1b, u32* ctr) {
;     ...
;         if (tl + 2 < 16) {
;           dn2_issue(WA, pl + (tl + 2) * 128, wbase, grp);
;           xa0 = *(const u32x4*)(xb0 + (size_t)(tl + 2) * 1024); xa1 = *(const u32x4*)(xb0 + (size_t)(tl + 2) * 1024 + 8);
;         }
	v_add_f32_e32 v167, v167, v183
	v_cndmask_b32_e64 v183, v173, v189, s[10:11]
	ds_bpermute_b32 v183, v157, v183
	v_cndmask_b32_e64 v173, v189, v173, s[10:11]
	v_cndmask_b32_e64 v175, v240, v175, s[10:11]
	ds_bpermute_b32 v203, v157, v203
	ds_bpermute_b32 v204, v157, v204
	s_waitcnt lgkmcnt(2)
	v_add_f32_e32 v173, v173, v183
	v_cndmask_b32_e64 v183, v179, v238, s[10:11]
	ds_bpermute_b32 v187, v157, v187
	v_add_f32_e32 v175, v175, v185
	ds_bpermute_b32 v183, v157, v183
	v_cndmask_b32_e64 v185, v181, v202, s[10:11]
	ds_bpermute_b32 v185, v157, v185
	v_cndmask_b32_e64 v177, v241, v177, s[10:11]
	v_cndmask_b32_e64 v179, v238, v179, s[10:11]
	s_waitcnt lgkmcnt(4)
	v_add_f32_e32 v169, v169, v203
	s_waitcnt lgkmcnt(3)
	v_add_f32_e32 v171, v171, v204
	s_waitcnt lgkmcnt(2)
	v_add_f32_e32 v177, v177, v187
	s_waitcnt lgkmcnt(1)
	v_add_f32_e32 v179, v179, v183
	v_cndmask_b32_e64 v181, v202, v181, s[10:11]
	v_cndmask_b32_e64 v187, v167, v175, s[12:13]
	s_waitcnt lgkmcnt(0)
	v_add_f32_e32 v181, v181, v185
	v_cndmask_b32_e64 v167, v175, v167, s[12:13]
	v_cndmask_b32_e64 v175, v169, v177, s[12:13]
	v_cndmask_b32_e64 v169, v177, v169, s[12:13]
	v_cndmask_b32_e64 v177, v171, v179, s[12:13]
	ds_bpermute_b32 v187, v159, v187
	ds_bpermute_b32 v177, v159, v177
	v_cndmask_b32_e64 v183, v173, v181, s[12:13]
	ds_bpermute_b32 v175, v159, v175
	ds_bpermute_b32 v183, v159, v183
	v_cndmask_b32_e64 v171, v179, v171, s[12:13]
	s_waitcnt lgkmcnt(3)
	v_add_f32_e32 v167, v167, v187
	s_waitcnt lgkmcnt(2)
	v_add_f32_e32 v171, v171, v177
	v_cndmask_b32_e64 v173, v181, v173, s[12:13]
	s_waitcnt lgkmcnt(1)
	v_add_f32_e32 v169, v169, v175
	s_waitcnt lgkmcnt(0)
	v_add_f32_e32 v173, v173, v183
	v_cndmask_b32_e64 v175, v167, v171, s[14:15]
	ds_bpermute_b32 v175, v163, v175
	v_cndmask_b32_e64 v177, v169, v173, s[14:15]
	ds_bpermute_b32 v177, v163, v177
	v_cndmask_b32_e64 v167, v171, v167, s[14:15]
	v_cndmask_b32_e64 v169, v173, v169, s[14:15]
	s_waitcnt lgkmcnt(1)
	v_add_f32_e32 v167, v167, v175
	s_waitcnt lgkmcnt(0)
	v_add_f32_e32 v169, v169, v177
	global_store_dword v[200:201], v167, off offset:-512
	global_store_dword v[200:201], v169, off offset:-480
	s_cmp_gt_u32 s46, 13
	s_cselect_b64 s[28:29], -1, 0
	s_and_b64 vcc, exec, s[28:29]
	s_cbranch_vccnz .LBB0_693
	ds_read2_b32 v[2:3], v165 offset0:128 offset1:136
	ds_read2_b32 v[10:11], v165 offset0:144 offset1:152
	ds_read2_b32 v[18:19], v165 offset0:160 offset1:168
	ds_read2_b32 v[26:27], v165 offset0:176 offset1:184
	ds_read2_b32 v[34:35], v165 offset0:192 offset1:200
	ds_read2_b32 v[42:43], v165 offset0:208 offset1:216
	ds_read2_b32 v[50:51], v165 offset0:224 offset1:232
	ds_read2_b32 v[58:59], v165 offset0:240 offset1:248
	s_waitcnt lgkmcnt(7)
	v_lshl_add_u32 v6, v3, 10, v250
	v_lshl_add_u32 v2, v2, 10, v250
	global_load_dwordx4 v[2:5], v2, s[98:99]
	global_load_dwordx4 v[6:9], v6, s[98:99]
	s_waitcnt lgkmcnt(6)
	v_lshl_add_u32 v14, v11, 10, v250
	v_lshl_add_u32 v10, v10, 10, v250
	global_load_dwordx4 v[10:13], v10, s[98:99]
	global_load_dwordx4 v[14:17], v14, s[98:99]
	s_waitcnt lgkmcnt(5)
	v_lshl_add_u32 v22, v19, 10, v250
	v_lshl_add_u32 v18, v18, 10, v250
	global_load_dwordx4 v[18:21], v18, s[98:99]
	global_load_dwordx4 v[22:25], v22, s[98:99]
	s_waitcnt lgkmcnt(4)
	v_lshl_add_u32 v30, v27, 10, v250
	v_lshl_add_u32 v26, v26, 10, v250
	global_load_dwordx4 v[26:29], v26, s[98:99]
	global_load_dwordx4 v[30:33], v30, s[98:99]
	s_waitcnt lgkmcnt(3)
	v_lshl_add_u32 v38, v35, 10, v250
	v_lshl_add_u32 v34, v34, 10, v250
	global_load_dwordx4 v[34:37], v34, s[98:99]
	global_load_dwordx4 v[38:41], v38, s[98:99]
	s_waitcnt lgkmcnt(2)
	v_lshl_add_u32 v46, v43, 10, v250
	v_lshl_add_u32 v42, v42, 10, v250
	global_load_dwordx4 v[42:45], v42, s[98:99]
	global_load_dwordx4 v[46:49], v46, s[98:99]
	s_waitcnt lgkmcnt(1)
	v_lshl_add_u32 v54, v51, 10, v250
	v_lshl_add_u32 v50, v50, 10, v250
	global_load_dwordx4 v[50:53], v50, s[98:99]
	global_load_dwordx4 v[54:57], v54, s[98:99]
	s_waitcnt lgkmcnt(0)
	v_lshl_add_u32 v62, v59, 10, v250
	v_lshl_add_u32 v58, v58, 10, v250
	global_load_dwordx4 v[58:61], v58, s[98:99]
	global_load_dwordx4 v[62:65], v62, s[98:99]
	s_nop 0
	global_load_dwordx4 v[66:69], v[198:199], off offset:16
	global_load_dwordx4 v[70:73], v[198:199], off
	s_branch .LBB0_693

;     ...
;   for (int tile = t_start; tile < t_total; tile += t_step) {
;     int mt, nt;
;     if (cntS) { mt = tile / cntS; nt = xi + 8 * (tile % cntS); } else { mt = tile / Ntiles; nt = tile % Ntiles; }
;     const int m0 = mt * 128, n0 = nt * 128;
.LBB0_1317:
	s_cmp_lg_u32 s26, 0x200
	s_cbranch_scc1 .Lmy_xr_plain_op1
	s_and_b32 s0, s21, 7
	s_bfe_u32 s1, s21, 0x60003
	s_lshr_b32 s11, s21, 9
	s_lshl_b32 s11, s11, 6
	s_add_i32 s1, s1, s11
	s_lshr_b32 s11, s1, 3
	s_lshl_b32 s11, s11, 3
	s_and_b32 s1, s1, 7
	s_add_i32 s11, s11, s0
	s_mov_b32 s0, s1
	s_mov_b32 s1, s11
	s_branch .Lmy_xr_join_op1

; DI int opaque_tid() { int t = threadIdx.x; asm volatile("" : "+v"(t)); return t; }
; DI void gemm_mainloop(const bf16* __restrict__ A, int lda, const bf16* __restrict__ Bt, int ldb, int K, int m0, int n0,
;                       bf16* As, bf16* Bs, f32x16& acc0, f32x16& acc1, f32x16& acc2, f32x16& acc3) {
;   const int tid = opaque_tid(), lane = tid & 63, w = tid >> 6, r = lane & 31, g = lane >> 5;
;   const int lrow = tid >> 3, lcc = (tid & 7) * 8;
;   const bf16* ap = A + (size_t)(m0 + lrow) * lda + lcc;
;   const bf16* bp = Bt + (size_t)(n0 + lrow) * ldb + lcc;
;   GTile t0, t1;
;   asm volatile("" ::: "memory");
;   const int nkt = K >> 6;
;   int kb = ((((m0 >> 7) * 5 + (n0 >> 7) * 3) >> 1) % nkt) << 6;
;     ...
;   gt_load(t0, ap, bp, lda, ldb, KW(0));
;   gt_load(t1, ap, bp, lda, ldb, KW(64));
; #pragma unroll
;   for (int i = 0; i < 16; ++i) { acc0[i] = 0.f; acc1[i] = 0.f; acc2[i] = 0.f; acc3[i] = 0.f; }
;   bf16* asw = As + lrow * LDT + lcc;
;   bf16* bsw = Bs + lrow * LDT + lcc;
;   const bf16* asr = As + (32 * w + r) * LDT + g * 8;
;   const bf16* bsr = Bs + r * LDT + g * 8;
.Lmy_xr_join_op1:
	s_lshl_b32 s11, s1, 7
	s_lshl_b32 s10, s0, 7
	v_mov_b32_e32 v8, v160
	s_mul_i32 s1, s1, 5
	s_mul_i32 s0, s0, 3
	s_add_i32 s0, s0, s1
	v_ashrrev_i32_e32 v9, 3, v8
	v_add_u32_e32 v0, s11, v9
	s_ashr_i32 s1, s0, 1
	s_ashr_i32 s0, s0, 31
	v_ashrrev_i32_e32 v1, 31, v0
	s_lshr_b32 s0, s0, 28
	v_lshlrev_b64 v[0:1], 11, v[0:1]
	v_lshlrev_b32_e32 v2, 4, v8
	s_add_i32 s0, s1, s0
	v_lshl_add_u64 v[0:1], s[36:37], 0, v[0:1]
	v_and_b32_e32 v128, 0x70, v2
	s_and_b32 s0, s0, -16
	v_lshl_add_u64 v[132:133], v[0:1], 0, v[128:129]
	v_add_u32_e32 v0, s10, v9
	s_sub_i32 s0, s1, s0
	v_ashrrev_i32_e32 v1, 31, v0
	s_lshl_b32 s12, s0, 6
	v_lshlrev_b64 v[0:1], 11, v[0:1]
	s_ashr_i32 s13, s12, 31
	v_lshl_add_u64 v[0:1], s[8:9], 0, v[0:1]
	s_lshl_b64 s[6:7], s[12:13], 1
	v_lshl_add_u64 v[134:135], v[0:1], 0, v[128:129]
	v_lshl_add_u64 v[0:1], v[132:133], 0, s[6:7]
	v_add_co_u32_e32 v4, vcc, s4, v0
	v_lshl_add_u64 v[2:3], v[134:135], 0, s[6:7]
	s_nop 0
	v_addc_co_u32_e32 v5, vcc, 0, v1, vcc
	v_add_co_u32_e32 v6, vcc, s5, v0
	s_cmp_lt_i32 s0, 15
	s_nop 0
	v_addc_co_u32_e32 v7, vcc, 0, v1, vcc
	global_load_dwordx4 v[64:67], v[4:5], off
	global_load_dwordx4 v[68:71], v[6:7], off
	v_add_co_u32_e32 v4, vcc, s18, v0
	global_load_dwordx4 v[72:75], v[0:1], off
	global_load_dwordx4 v[76:79], v[2:3], off
	v_addc_co_u32_e32 v5, vcc, 0, v1, vcc
	v_add_co_u32_e32 v6, vcc, s4, v2
	s_cselect_b32 s7, 0, -1
	s_nop 0
	v_addc_co_u32_e32 v7, vcc, 0, v3, vcc
	global_load_dwordx4 v[80:83], v[4:5], off
	global_load_dwordx4 v[84:87], v[6:7], off
	v_add_co_u32_e32 v4, vcc, s5, v2
	s_cselect_b32 s6, 0, 0xfffff800
	s_nop 0
	v_addc_co_u32_e32 v5, vcc, 0, v3, vcc
	v_add_co_u32_e32 v6, vcc, s18, v2
	v_lshl_add_u64 v[0:1], v[0:1], 0, s[6:7]
	s_nop 0
	v_addc_co_u32_e32 v7, vcc, 0, v3, vcc
	global_load_dwordx4 v[96:99], v[4:5], off
	global_load_dwordx4 v[100:103], v[6:7], off
	v_add_co_u32_e32 v4, vcc, s4, v0
	v_lshl_add_u64 v[2:3], v[2:3], 0, s[6:7]
	s_nop 0
	v_addc_co_u32_e32 v5, vcc, 0, v1, vcc
	v_add_co_u32_e32 v6, vcc, s5, v0
	v_mad_u64_u32 v[136:137], s[6:7], v9, s19, v[128:129]
	s_nop 0
	v_addc_co_u32_e32 v7, vcc, 0, v1, vcc
	global_load_dwordx4 v[88:91], v[4:5], off offset:128
	global_load_dwordx4 v[92:95], v[6:7], off offset:128
	v_add_co_u32_e32 v4, vcc, s18, v0
	global_load_dwordx4 v[104:107], v[0:1], off offset:128
	global_load_dwordx4 v[108:111], v[2:3], off offset:128
	v_addc_co_u32_e32 v5, vcc, 0, v1, vcc
	v_add_co_u32_e32 v0, vcc, s4, v2
	s_sub_i32 s25, 0x400, s12
	s_nop 0
	v_addc_co_u32_e32 v1, vcc, 0, v3, vcc
	global_load_dwordx4 v[112:115], v[4:5], off offset:128
	global_load_dwordx4 v[116:119], v[0:1], off offset:128
	v_add_co_u32_e32 v0, vcc, s5, v2
	s_sub_i32 s28, 0x340, s12
	s_nop 0
	v_addc_co_u32_e32 v1, vcc, 0, v3, vcc
	v_add_co_u32_e32 v2, vcc, s18, v2
	s_mov_b64 s[14:15], 0
	s_nop 0
	v_addc_co_u32_e32 v3, vcc, 0, v3, vcc
	global_load_dwordx4 v[120:123], v[0:1], off offset:128
	global_load_dwordx4 v[124:127], v[2:3], off offset:128
	v_and_b32_e32 v1, 31, v8
	v_lshrrev_b32_e32 v0, 1, v8
	v_and_or_b32 v2, v0, s20, v1
	v_and_b32_e32 v0, 16, v0
	v_mad_u64_u32 v[138:139], s[6:7], v2, s19, v[0:1]
	v_mad_u32_u24 v128, v1, s19, v0
	v_mov_b32_e32 v0, 0
	v_mov_b32_e32 v1, v129
	v_mov_b32_e32 v2, v129
	v_mov_b32_e32 v3, v129
	v_mov_b32_e32 v4, v129
	v_mov_b32_e32 v5, v129
	v_mov_b32_e32 v6, v129
	v_mov_b32_e32 v7, v129
	v_mov_b32_e32 v8, v129
	v_mov_b32_e32 v9, v129
	v_mov_b32_e32 v10, v129
	v_mov_b32_e32 v11, v129
	v_mov_b32_e32 v12, v129
	v_mov_b32_e32 v13, v129
	v_mov_b32_e32 v14, v129
	v_mov_b32_e32 v15, v129
	v_mov_b32_e32 v16, 0
	v_mov_b32_e32 v17, v129
	v_mov_b32_e32 v18, v129
	v_mov_b32_e32 v19, v129
	v_mov_b32_e32 v20, v129
	v_mov_b32_e32 v21, v129
	v_mov_b32_e32 v22, v129
	v_mov_b32_e32 v23, v129
	v_mov_b32_e32 v24, v129
	v_mov_b32_e32 v25, v129
	v_mov_b32_e32 v26, v129
	v_mov_b32_e32 v27, v129
	v_mov_b32_e32 v28, v129
	v_mov_b32_e32 v29, v129
	v_mov_b32_e32 v30, v129
	v_mov_b32_e32 v31, v129
	v_mov_b32_e32 v32, 0
	v_mov_b32_e32 v33, v129
	v_mov_b32_e32 v34, v129
	v_mov_b32_e32 v35, v129
	v_mov_b32_e32 v36, v129
	v_mov_b32_e32 v37, v129
	v_mov_b32_e32 v38, v129
	v_mov_b32_e32 v39, v129
	v_mov_b32_e32 v40, v129
	v_mov_b32_e32 v41, v129
	v_mov_b32_e32 v42, v129
	v_mov_b32_e32 v43, v129
	v_mov_b32_e32 v44, v129
	v_mov_b32_e32 v45, v129
	v_mov_b32_e32 v46, v129
	v_mov_b32_e32 v47, v129
	v_mov_b32_e32 v48, 0
	v_mov_b32_e32 v49, v129
	v_mov_b32_e32 v50, v129
	v_mov_b32_e32 v51, v129
	v_mov_b32_e32 v52, v129
	v_mov_b32_e32 v53, v129
	v_mov_b32_e32 v54, v129
	v_mov_b32_e32 v55, v129
	v_mov_b32_e32 v56, v129
	v_mov_b32_e32 v57, v129
	v_mov_b32_e32 v58, v129
	v_mov_b32_e32 v59, v129
	v_mov_b32_e32 v60, v129
	v_mov_b32_e32 v61, v129
	v_mov_b32_e32 v62, v129
	v_mov_b32_e32 v63, v129
	s_branch .LBB0_1319

; DI void dn2_issue(u32x4 (&W)[16], const int* pl, const unsigned char* wbase, int grp) {
; #pragma unroll
;   for (int j = 0; j < 16; ++j) W[j] = *(const u32x4*)(wbase + (size_t)pl[8 * j + grp] * 1024);
; DI void peer_down2_phase(const Params& p, unsigned char* smem, int layer, const bf16* __restrict__ x1b, u32* ctr) {
;     ...
;       const int t0 = item * 64 + 16 * w;
;       const unsigned char* wbase = wd + slice * 128 + c * 16;
.LBB0_1503:
	s_add_i32 s0, s31, s4
	s_and_b32 s2, s0, 7
	s_and_b64 s[0:1], s[18:19], exec
	s_cselect_b32 s0, s2, s30
	s_lshl_b32 s1, s2, 2
	s_add_u32 s38, s5, s1
	s_addc_u32 s39, s25, 0
	s_lshl_b32 s28, s0, 7
	s_ashr_i32 s29, s28, 31
	s_ashr_i32 s1, s0, 31
	v_lshl_add_u64 v[190:191], v[148:149], 0, s[28:29]
	s_nop 0
	v_readfirstlane_b32 s98, v190
	v_readfirstlane_b32 s99, v191
	v_and_b32_e32 v250, 7, v160
	v_lshlrev_b32_e32 v250, 4, v250
	s_lshl_b64 s[28:29], s[28:29], 1
	s_lshl_b64 s[0:1], s[0:1], 23
	v_lshl_add_u64 v[192:193], v[150:151], 0, s[28:29]
	v_lshl_add_u64 v[194:195], v[152:153], 0, s[28:29]
	v_lshl_add_u64 v[196:197], v[154:155], 0, s[0:1]
	v_mov_b32_e32 v2, v0
	s_branch .LBB0_1506

; DI float bflo(u32 u) { return __uint_as_float(u << 16); }
; DI float bfhi(u32 u) { return __uint_as_float(u & 0xffff0000u); }
; DI void dn2_issue(u32x4 (&W)[16], const int* pl, const unsigned char* wbase, int grp) {
; #pragma unroll
;   for (int j = 0; j < 16; ++j) W[j] = *(const u32x4*)(wbase + (size_t)pl[8 * j + grp] * 1024);
; }
; DI void dn2_math(const u32x4 (&W)[16], u32x4 x0, u32x4 x1, float* __restrict__ parow, int lane) {
;   f2 xf[8];
; #pragma unroll
;   for (int q = 0; q < 4; ++q) { xf[q] = f2{bflo(x0[q]), bfhi(x0[q])}; xf[4 + q] = f2{bflo(x1[q]), bfhi(x1[q])}; }
;   float pv[16];
; #pragma unroll
;   for (int j = 0; j < 16; ++j) {
;     f2 s2 = {0.f, 0.f};
; #pragma unroll
;     for (int d = 0; d < 4; ++d) {
;       f2 lo = __builtin_amdgcn_cvt_pk_f32_fp8((int)W[j][d], false);
;       f2 hi = __builtin_amdgcn_cvt_pk_f32_fp8((int)W[j][d], true);
;       s2 = lo * xf[2 * d] + s2;
;       s2 = hi * xf[2 * d + 1] + s2;
;     }
;     pv[j] = s2.x + s2.y;
;   }
; DI void peer_down2_phase(const Params& p, unsigned char* smem, int layer, const bf16* __restrict__ x1b, u32* ctr) {
;     ...
;       for (int tl = 0; tl < 16; tl += 2) {
;         dn2_issue(WB, pl + (tl + 1) * 128, wbase, grp);
;         xb_0 = *(const u32x4*)(xb0 + (size_t)(tl + 1) * 1024); xb_1 = *(const u32x4*)(xb0 + (size_t)(tl + 1) * 1024 + 8);
;         __builtin_amdgcn_sched_barrier(0);
;         dn2_math(WA, xa0, xa1, pbase + (size_t)tl * 128, lane);
.LBB0_1517:
	ds_read2_b32 v[134:135], v165 offset1:8
	ds_read2_b32 v[126:127], v165 offset0:16 offset1:24
	ds_read2_b32 v[118:119], v165 offset0:32 offset1:40
	ds_read2_b32 v[110:111], v165 offset0:48 offset1:56
	ds_read2_b32 v[102:103], v165 offset0:64 offset1:72
	ds_read2_b32 v[94:95], v165 offset0:80 offset1:88
	ds_read2_b32 v[86:87], v165 offset0:96 offset1:104
	ds_read2_b32 v[78:79], v165 offset0:112 offset1:120
	s_waitcnt lgkmcnt(7)
	v_lshl_add_u32 v130, v135, 10, v250
	v_lshl_add_u32 v134, v134, 10, v250
	global_load_dwordx4 v[134:137], v134, s[98:99]
	global_load_dwordx4 v[130:133], v130, s[98:99]
	s_waitcnt lgkmcnt(6)
	v_lshl_add_u32 v122, v127, 10, v250
	v_lshl_add_u32 v126, v126, 10, v250
	global_load_dwordx4 v[126:129], v126, s[98:99]
	global_load_dwordx4 v[122:125], v122, s[98:99]
	s_waitcnt lgkmcnt(5)
	v_lshl_add_u32 v114, v119, 10, v250
	v_lshl_add_u32 v118, v118, 10, v250
	global_load_dwordx4 v[118:121], v118, s[98:99]
	global_load_dwordx4 v[114:117], v114, s[98:99]
	s_waitcnt lgkmcnt(4)
	v_lshl_add_u32 v106, v111, 10, v250
	v_lshl_add_u32 v110, v110, 10, v250
	global_load_dwordx4 v[110:113], v110, s[98:99]
	global_load_dwordx4 v[106:109], v106, s[98:99]
	s_waitcnt lgkmcnt(3)
	v_lshl_add_u32 v98, v103, 10, v250
	v_lshl_add_u32 v102, v102, 10, v250
	global_load_dwordx4 v[102:105], v102, s[98:99]
	global_load_dwordx4 v[98:101], v98, s[98:99]
	s_waitcnt lgkmcnt(2)
	v_lshl_add_u32 v90, v95, 10, v250
	v_lshl_add_u32 v94, v94, 10, v250
	global_load_dwordx4 v[94:97], v94, s[98:99]
	global_load_dwordx4 v[90:93], v90, s[98:99]
	s_waitcnt lgkmcnt(1)
	v_lshl_add_u32 v82, v87, 10, v250
	v_lshl_add_u32 v86, v86, 10, v250
	global_load_dwordx4 v[86:89], v86, s[98:99]
	global_load_dwordx4 v[82:85], v82, s[98:99]
	s_waitcnt lgkmcnt(0)
	v_lshl_add_u32 v74, v79, 10, v250
	v_lshl_add_u32 v78, v78, 10, v250
	global_load_dwordx4 v[78:81], v78, s[98:99]
	global_load_dwordx4 v[74:77], v74, s[98:99]
	s_nop 0
	global_load_dwordx4 v[138:141], v[198:199], off offset:-2032
	global_load_dwordx4 v[142:145], v[198:199], off offset:-2048
	s_waitcnt vmcnt(35)
	v_cvt_pk_f32_fp8_e32 v[230:231], v2
	v_cvt_pk_f32_fp8_sdwa v[232:233], v2 src0_sel:WORD_1
	v_cvt_pk_f32_fp8_e32 v[234:235], v3
	s_waitcnt vmcnt(18)
	v_lshlrev_b32_e32 v210, 16, v70
	v_and_b32_e32 v211, 0xffff0000, v70
	v_cvt_pk_f32_fp8_sdwa v[236:237], v3 src0_sel:WORD_1
	v_lshlrev_b32_e32 v212, 16, v71
	v_and_b32_e32 v213, 0xffff0000, v71
	v_pk_fma_f32 v[230:231], v[230:231], v[210:211], 0 op_sel_hi:[1,1,0]
	v_lshlrev_b32_e32 v214, 16, v72
	v_and_b32_e32 v215, 0xffff0000, v72
	v_pk_fma_f32 v[230:231], v[232:233], v[212:213], v[230:231]
	v_cvt_pk_f32_fp8_e32 v[232:233], v4
	v_lshlrev_b32_e32 v216, 16, v73
	v_and_b32_e32 v217, 0xffff0000, v73
	v_pk_fma_f32 v[230:231], v[234:235], v[214:215], v[230:231]
	v_cvt_pk_f32_fp8_sdwa v[234:235], v4 src0_sel:WORD_1
	v_pk_fma_f32 v[230:231], v[236:237], v[216:217], v[230:231]
	v_cvt_pk_f32_fp8_e32 v[236:237], v5
	v_lshlrev_b32_e32 v202, 16, v66
	v_and_b32_e32 v203, 0xffff0000, v66
	v_cvt_pk_f32_fp8_sdwa v[238:239], v5 src0_sel:WORD_1
	v_lshlrev_b32_e32 v204, 16, v67
	v_and_b32_e32 v205, 0xffff0000, v67
	v_pk_fma_f32 v[230:231], v[232:233], v[202:203], v[230:231]
	v_lshlrev_b32_e32 v206, 16, v68
	v_and_b32_e32 v207, 0xffff0000, v68
	v_pk_fma_f32 v[230:231], v[234:235], v[204:205], v[230:231]
	v_lshlrev_b32_e32 v208, 16, v69
	v_and_b32_e32 v209, 0xffff0000, v69
	v_pk_fma_f32 v[230:231], v[236:237], v[206:207], v[230:231]
	v_cvt_pk_f32_fp8_sdwa v[232:233], v6 src0_sel:WORD_1
	v_pk_fma_f32 v[230:231], v[238:239], v[208:209], v[230:231]
	v_cvt_pk_f32_fp8_e32 v[234:235], v7
	v_add_f32_e32 v167, v230, v231
	v_cvt_pk_f32_fp8_e32 v[230:231], v6
	v_cvt_pk_f32_fp8_sdwa v[236:237], v7 src0_sel:WORD_1
	v_cvt_pk_f32_fp8_sdwa v[238:239], v9 src0_sel:WORD_1
	v_pk_fma_f32 v[230:231], v[230:231], v[210:211], 0 op_sel_hi:[1,1,0]
	s_nop 0
	v_pk_fma_f32 v[230:231], v[232:233], v[212:213], v[230:231]
	v_cvt_pk_f32_fp8_e32 v[232:233], v8
	v_pk_fma_f32 v[230:231], v[234:235], v[214:215], v[230:231]
	v_cvt_pk_f32_fp8_sdwa v[234:235], v8 src0_sel:WORD_1
	v_pk_fma_f32 v[230:231], v[236:237], v[216:217], v[230:231]
	v_cvt_pk_f32_fp8_e32 v[236:237], v9
	v_pk_fma_f32 v[230:231], v[232:233], v[202:203], v[230:231]
	v_cvt_pk_f32_fp8_sdwa v[232:233], v10 src0_sel:WORD_1
	v_pk_fma_f32 v[230:231], v[234:235], v[204:205], v[230:231]
	v_cvt_pk_f32_fp8_e32 v[234:235], v11
	v_pk_fma_f32 v[230:231], v[236:237], v[206:207], v[230:231]
	v_cvt_pk_f32_fp8_sdwa v[236:237], v11 src0_sel:WORD_1
	v_pk_fma_f32 v[230:231], v[238:239], v[208:209], v[230:231]
	v_cvt_pk_f32_fp8_sdwa v[238:239], v13 src0_sel:WORD_1
	v_add_f32_e32 v169, v230, v231
	v_cvt_pk_f32_fp8_e32 v[230:231], v10
	v_pk_fma_f32 v[230:231], v[230:231], v[210:211], 0 op_sel_hi:[1,1,0]
	s_nop 0
	v_pk_fma_f32 v[230:231], v[232:233], v[212:213], v[230:231]
	v_cvt_pk_f32_fp8_e32 v[232:233], v12
	v_pk_fma_f32 v[230:231], v[234:235], v[214:215], v[230:231]
	v_cvt_pk_f32_fp8_sdwa v[234:235], v12 src0_sel:WORD_1
	v_pk_fma_f32 v[230:231], v[236:237], v[216:217], v[230:231]
	v_cvt_pk_f32_fp8_e32 v[236:237], v13
	v_pk_fma_f32 v[230:231], v[232:233], v[202:203], v[230:231]
	v_cvt_pk_f32_fp8_sdwa v[232:233], v14 src0_sel:WORD_1
	v_pk_fma_f32 v[230:231], v[234:235], v[204:205], v[230:231]
	v_cvt_pk_f32_fp8_e32 v[234:235], v15
	v_pk_fma_f32 v[230:231], v[236:237], v[206:207], v[230:231]
	v_cvt_pk_f32_fp8_sdwa v[236:237], v15 src0_sel:WORD_1
	v_pk_fma_f32 v[230:231], v[238:239], v[208:209], v[230:231]
	v_cvt_pk_f32_fp8_sdwa v[238:239], v17 src0_sel:WORD_1
	v_add_f32_e32 v171, v230, v231
	v_cvt_pk_f32_fp8_e32 v[230:231], v14
; DI float bflo(u32 u) { return __uint_as_float(u << 16); }
; DI float bfhi(u32 u) { return __uint_as_float(u & 0xffff0000u); }
; DI void dn2_math(const u32x4 (&W)[16], u32x4 x0, u32x4 x1, float* __restrict__ parow, int lane) {
;   f2 xf[8];
; #pragma unroll
;   for (int q = 0; q < 4; ++q) { xf[q] = f2{bflo(x0[q]), bfhi(x0[q])}; xf[4 + q] = f2{bflo(x1[q]), bfhi(x1[q])}; }
;   float pv[16];
; #pragma unroll
;   for (int j = 0; j < 16; ++j) {
;     f2 s2 = {0.f, 0.f};
; #pragma unroll
;     for (int d = 0; d < 4; ++d) {
;       f2 lo = __builtin_amdgcn_cvt_pk_f32_fp8((int)W[j][d], false);
;       f2 hi = __builtin_amdgcn_cvt_pk_f32_fp8((int)W[j][d], true);
;       s2 = lo * xf[2 * d] + s2;
;       s2 = hi * xf[2 * d + 1] + s2;
;     }
;     pv[j] = s2.x + s2.y;
;   }
	v_pk_fma_f32 v[230:231], v[230:231], v[210:211], 0 op_sel_hi:[1,1,0]
	s_nop 0
	v_pk_fma_f32 v[230:231], v[232:233], v[212:213], v[230:231]
	v_cvt_pk_f32_fp8_e32 v[232:233], v16
	v_pk_fma_f32 v[230:231], v[234:235], v[214:215], v[230:231]
	v_cvt_pk_f32_fp8_sdwa v[234:235], v16 src0_sel:WORD_1
	v_pk_fma_f32 v[230:231], v[236:237], v[216:217], v[230:231]
	v_cvt_pk_f32_fp8_e32 v[236:237], v17
	v_pk_fma_f32 v[230:231], v[232:233], v[202:203], v[230:231]
	v_cvt_pk_f32_fp8_sdwa v[232:233], v18 src0_sel:WORD_1
	v_pk_fma_f32 v[230:231], v[234:235], v[204:205], v[230:231]
	v_cvt_pk_f32_fp8_e32 v[234:235], v19
	v_pk_fma_f32 v[230:231], v[236:237], v[206:207], v[230:231]
	v_cvt_pk_f32_fp8_sdwa v[236:237], v19 src0_sel:WORD_1
	v_pk_fma_f32 v[230:231], v[238:239], v[208:209], v[230:231]
	v_cvt_pk_f32_fp8_sdwa v[238:239], v21 src0_sel:WORD_1
	v_add_f32_e32 v173, v230, v231
	v_cvt_pk_f32_fp8_e32 v[230:231], v18
	v_pk_fma_f32 v[230:231], v[230:231], v[210:211], 0 op_sel_hi:[1,1,0]
	s_nop 0
	v_pk_fma_f32 v[230:231], v[232:233], v[212:213], v[230:231]
	v_cvt_pk_f32_fp8_e32 v[232:233], v20
	v_pk_fma_f32 v[230:231], v[234:235], v[214:215], v[230:231]
	v_cvt_pk_f32_fp8_sdwa v[234:235], v20 src0_sel:WORD_1
	v_pk_fma_f32 v[230:231], v[236:237], v[216:217], v[230:231]
	v_cvt_pk_f32_fp8_e32 v[236:237], v21
	v_pk_fma_f32 v[230:231], v[232:233], v[202:203], v[230:231]
	v_cvt_pk_f32_fp8_sdwa v[232:233], v22 src0_sel:WORD_1
	v_pk_fma_f32 v[230:231], v[234:235], v[204:205], v[230:231]
	v_cvt_pk_f32_fp8_e32 v[234:235], v23
	v_pk_fma_f32 v[230:231], v[236:237], v[206:207], v[230:231]
	v_cvt_pk_f32_fp8_sdwa v[236:237], v23 src0_sel:WORD_1
	v_pk_fma_f32 v[230:231], v[238:239], v[208:209], v[230:231]
	v_cvt_pk_f32_fp8_sdwa v[238:239], v25 src0_sel:WORD_1
	v_add_f32_e32 v175, v230, v231
	v_cvt_pk_f32_fp8_e32 v[230:231], v22
	v_pk_fma_f32 v[230:231], v[230:231], v[210:211], 0 op_sel_hi:[1,1,0]
	s_nop 0
	v_pk_fma_f32 v[230:231], v[232:233], v[212:213], v[230:231]
	v_cvt_pk_f32_fp8_e32 v[232:233], v24
	v_pk_fma_f32 v[230:231], v[234:235], v[214:215], v[230:231]
	v_cvt_pk_f32_fp8_sdwa v[234:235], v24 src0_sel:WORD_1
	v_pk_fma_f32 v[230:231], v[236:237], v[216:217], v[230:231]
	v_cvt_pk_f32_fp8_e32 v[236:237], v25
	v_pk_fma_f32 v[230:231], v[232:233], v[202:203], v[230:231]
	v_cvt_pk_f32_fp8_sdwa v[232:233], v26 src0_sel:WORD_1
	v_pk_fma_f32 v[230:231], v[234:235], v[204:205], v[230:231]
	v_cvt_pk_f32_fp8_e32 v[234:235], v27
	v_pk_fma_f32 v[230:231], v[236:237], v[206:207], v[230:231]
	v_cvt_pk_f32_fp8_sdwa v[236:237], v27 src0_sel:WORD_1
	v_pk_fma_f32 v[230:231], v[238:239], v[208:209], v[230:231]
	v_cvt_pk_f32_fp8_sdwa v[238:239], v29 src0_sel:WORD_1
	v_add_f32_e32 v177, v230, v231
	v_cvt_pk_f32_fp8_e32 v[230:231], v26
	v_pk_fma_f32 v[230:231], v[230:231], v[210:211], 0 op_sel_hi:[1,1,0]
	s_nop 0
	v_pk_fma_f32 v[230:231], v[232:233], v[212:213], v[230:231]
	v_cvt_pk_f32_fp8_e32 v[232:233], v28
	v_pk_fma_f32 v[230:231], v[234:235], v[214:215], v[230:231]
	v_cvt_pk_f32_fp8_sdwa v[234:235], v28 src0_sel:WORD_1
	v_pk_fma_f32 v[230:231], v[236:237], v[216:217], v[230:231]
	v_cvt_pk_f32_fp8_e32 v[236:237], v29
	v_pk_fma_f32 v[230:231], v[232:233], v[202:203], v[230:231]
	v_cvt_pk_f32_fp8_sdwa v[232:233], v30 src0_sel:WORD_1
	v_pk_fma_f32 v[230:231], v[234:235], v[204:205], v[230:231]
	v_cvt_pk_f32_fp8_e32 v[234:235], v31
	v_pk_fma_f32 v[230:231], v[236:237], v[206:207], v[230:231]
	v_cvt_pk_f32_fp8_sdwa v[236:237], v31 src0_sel:WORD_1
	v_pk_fma_f32 v[230:231], v[238:239], v[208:209], v[230:231]
	v_cvt_pk_f32_fp8_sdwa v[238:239], v33 src0_sel:WORD_1
	v_add_f32_e32 v179, v230, v231
	v_cvt_pk_f32_fp8_e32 v[230:231], v30
	v_pk_fma_f32 v[230:231], v[230:231], v[210:211], 0 op_sel_hi:[1,1,0]
	s_nop 0
	v_pk_fma_f32 v[230:231], v[232:233], v[212:213], v[230:231]
	v_cvt_pk_f32_fp8_e32 v[232:233], v32
	v_pk_fma_f32 v[230:231], v[234:235], v[214:215], v[230:231]
	v_cvt_pk_f32_fp8_sdwa v[234:235], v32 src0_sel:WORD_1
	v_pk_fma_f32 v[230:231], v[236:237], v[216:217], v[230:231]
	v_cvt_pk_f32_fp8_e32 v[236:237], v33
	v_pk_fma_f32 v[230:231], v[232:233], v[202:203], v[230:231]
	v_cvt_pk_f32_fp8_sdwa v[232:233], v34 src0_sel:WORD_1
	v_pk_fma_f32 v[230:231], v[234:235], v[204:205], v[230:231]
	v_cvt_pk_f32_fp8_e32 v[234:235], v35
	v_pk_fma_f32 v[230:231], v[236:237], v[206:207], v[230:231]
	v_cvt_pk_f32_fp8_sdwa v[236:237], v35 src0_sel:WORD_1
	v_pk_fma_f32 v[230:231], v[238:239], v[208:209], v[230:231]
	v_cvt_pk_f32_fp8_sdwa v[238:239], v37 src0_sel:WORD_1
	v_add_f32_e32 v181, v230, v231
	v_cvt_pk_f32_fp8_e32 v[230:231], v34
	v_pk_fma_f32 v[230:231], v[230:231], v[210:211], 0 op_sel_hi:[1,1,0]
	s_nop 0
	v_pk_fma_f32 v[230:231], v[232:233], v[212:213], v[230:231]
	v_cvt_pk_f32_fp8_e32 v[232:233], v36
	v_pk_fma_f32 v[230:231], v[234:235], v[214:215], v[230:231]
	v_cvt_pk_f32_fp8_sdwa v[234:235], v36 src0_sel:WORD_1
	v_pk_fma_f32 v[230:231], v[236:237], v[216:217], v[230:231]
	v_cvt_pk_f32_fp8_e32 v[236:237], v37
	v_pk_fma_f32 v[230:231], v[232:233], v[202:203], v[230:231]
	v_cvt_pk_f32_fp8_sdwa v[232:233], v38 src0_sel:WORD_1
	v_pk_fma_f32 v[230:231], v[234:235], v[204:205], v[230:231]
	v_cvt_pk_f32_fp8_e32 v[234:235], v39
	v_pk_fma_f32 v[230:231], v[236:237], v[206:207], v[230:231]
	v_cvt_pk_f32_fp8_sdwa v[236:237], v39 src0_sel:WORD_1
	v_pk_fma_f32 v[230:231], v[238:239], v[208:209], v[230:231]
	v_cvt_pk_f32_fp8_sdwa v[238:239], v41 src0_sel:WORD_1
	v_add_f32_e32 v183, v230, v231
	v_cvt_pk_f32_fp8_e32 v[230:231], v38
	v_pk_fma_f32 v[230:231], v[230:231], v[210:211], 0 op_sel_hi:[1,1,0]
	s_nop 0
	v_pk_fma_f32 v[230:231], v[232:233], v[212:213], v[230:231]
	v_cvt_pk_f32_fp8_e32 v[232:233], v40
; DI void dn2_math(const u32x4 (&W)[16], u32x4 x0, u32x4 x1, float* __restrict__ parow, int lane) {
;     ...
; #pragma unroll
;   for (int j = 0; j < 16; ++j) {
;     f2 s2 = {0.f, 0.f};
; #pragma unroll
;     for (int d = 0; d < 4; ++d) {
;       f2 lo = __builtin_amdgcn_cvt_pk_f32_fp8((int)W[j][d], false);
;       f2 hi = __builtin_amdgcn_cvt_pk_f32_fp8((int)W[j][d], true);
;       s2 = lo * xf[2 * d] + s2;
;       s2 = hi * xf[2 * d + 1] + s2;
;     }
;     pv[j] = s2.x + s2.y;
;   }
;   const bool b2 = lane & 4, b1 = lane & 2, b0 = lane & 1;
;   float q8[8];
; #pragma unroll
;   for (int i = 0; i < 8; ++i) { float snd = b2 ? pv[i] : pv[i + 8]; float kp = b2 ? pv[i + 8] : pv[i]; q8[i] = kp + __shfl_xor(snd, 4); }
	v_pk_fma_f32 v[230:231], v[234:235], v[214:215], v[230:231]
	v_cvt_pk_f32_fp8_sdwa v[234:235], v40 src0_sel:WORD_1
	v_pk_fma_f32 v[230:231], v[236:237], v[216:217], v[230:231]
	v_cvt_pk_f32_fp8_e32 v[236:237], v41
	v_pk_fma_f32 v[230:231], v[232:233], v[202:203], v[230:231]
	v_cvt_pk_f32_fp8_sdwa v[232:233], v42 src0_sel:WORD_1
	v_pk_fma_f32 v[230:231], v[234:235], v[204:205], v[230:231]
	v_cvt_pk_f32_fp8_e32 v[234:235], v43
	v_pk_fma_f32 v[230:231], v[236:237], v[206:207], v[230:231]
	v_cvt_pk_f32_fp8_sdwa v[236:237], v43 src0_sel:WORD_1
	v_pk_fma_f32 v[230:231], v[238:239], v[208:209], v[230:231]
	v_cvt_pk_f32_fp8_sdwa v[238:239], v45 src0_sel:WORD_1
	v_add_f32_e32 v185, v230, v231
	v_cvt_pk_f32_fp8_e32 v[230:231], v42
	v_pk_fma_f32 v[230:231], v[230:231], v[210:211], 0 op_sel_hi:[1,1,0]
	s_nop 0
	v_pk_fma_f32 v[230:231], v[232:233], v[212:213], v[230:231]
	v_cvt_pk_f32_fp8_e32 v[232:233], v44
	v_pk_fma_f32 v[230:231], v[234:235], v[214:215], v[230:231]
	v_cvt_pk_f32_fp8_sdwa v[234:235], v44 src0_sel:WORD_1
	v_pk_fma_f32 v[230:231], v[236:237], v[216:217], v[230:231]
	v_cvt_pk_f32_fp8_e32 v[236:237], v45
	v_pk_fma_f32 v[230:231], v[232:233], v[202:203], v[230:231]
	v_cvt_pk_f32_fp8_sdwa v[232:233], v46 src0_sel:WORD_1
	v_pk_fma_f32 v[230:231], v[234:235], v[204:205], v[230:231]
	v_cvt_pk_f32_fp8_e32 v[234:235], v47
	v_pk_fma_f32 v[230:231], v[236:237], v[206:207], v[230:231]
	v_cvt_pk_f32_fp8_sdwa v[236:237], v47 src0_sel:WORD_1
	v_pk_fma_f32 v[230:231], v[238:239], v[208:209], v[230:231]
	v_cvt_pk_f32_fp8_sdwa v[238:239], v49 src0_sel:WORD_1
	v_add_f32_e32 v187, v230, v231
	v_cvt_pk_f32_fp8_e32 v[230:231], v46
	v_pk_fma_f32 v[230:231], v[230:231], v[210:211], 0 op_sel_hi:[1,1,0]
	s_nop 0
	v_pk_fma_f32 v[230:231], v[232:233], v[212:213], v[230:231]
	v_cvt_pk_f32_fp8_e32 v[232:233], v48
	v_pk_fma_f32 v[230:231], v[234:235], v[214:215], v[230:231]
	v_cvt_pk_f32_fp8_sdwa v[234:235], v48 src0_sel:WORD_1
	v_pk_fma_f32 v[230:231], v[236:237], v[216:217], v[230:231]
	v_cvt_pk_f32_fp8_e32 v[236:237], v49
	v_pk_fma_f32 v[230:231], v[232:233], v[202:203], v[230:231]
	v_cvt_pk_f32_fp8_sdwa v[232:233], v50 src0_sel:WORD_1
	v_pk_fma_f32 v[230:231], v[234:235], v[204:205], v[230:231]
	v_cvt_pk_f32_fp8_e32 v[234:235], v51
	v_pk_fma_f32 v[230:231], v[236:237], v[206:207], v[230:231]
	v_cvt_pk_f32_fp8_sdwa v[236:237], v51 src0_sel:WORD_1
	v_pk_fma_f32 v[230:231], v[238:239], v[208:209], v[230:231]
	v_cvt_pk_f32_fp8_sdwa v[238:239], v53 src0_sel:WORD_1
	v_add_f32_e32 v189, v230, v231
	v_cvt_pk_f32_fp8_e32 v[230:231], v50
	v_pk_fma_f32 v[230:231], v[230:231], v[210:211], 0 op_sel_hi:[1,1,0]
	s_nop 0
	v_pk_fma_f32 v[230:231], v[232:233], v[212:213], v[230:231]
	v_cvt_pk_f32_fp8_e32 v[232:233], v52
	v_pk_fma_f32 v[230:231], v[234:235], v[214:215], v[230:231]
	v_cvt_pk_f32_fp8_sdwa v[234:235], v52 src0_sel:WORD_1
	v_pk_fma_f32 v[230:231], v[236:237], v[216:217], v[230:231]
	v_cvt_pk_f32_fp8_e32 v[236:237], v53
	v_pk_fma_f32 v[230:231], v[232:233], v[202:203], v[230:231]
	v_cvt_pk_f32_fp8_sdwa v[232:233], v54 src0_sel:WORD_1
	v_pk_fma_f32 v[230:231], v[234:235], v[204:205], v[230:231]
	v_cvt_pk_f32_fp8_e32 v[234:235], v55
	v_pk_fma_f32 v[230:231], v[236:237], v[206:207], v[230:231]
	v_cvt_pk_f32_fp8_sdwa v[236:237], v55 src0_sel:WORD_1
	v_pk_fma_f32 v[230:231], v[238:239], v[208:209], v[230:231]
	v_cvt_pk_f32_fp8_sdwa v[238:239], v57 src0_sel:WORD_1
	v_add_f32_e32 v229, v230, v231
	v_cvt_pk_f32_fp8_e32 v[230:231], v54
	v_pk_fma_f32 v[230:231], v[230:231], v[210:211], 0 op_sel_hi:[1,1,0]
	s_nop 0
	v_pk_fma_f32 v[230:231], v[232:233], v[212:213], v[230:231]
	v_cvt_pk_f32_fp8_e32 v[232:233], v56
	v_pk_fma_f32 v[230:231], v[234:235], v[214:215], v[230:231]
	v_cvt_pk_f32_fp8_sdwa v[234:235], v56 src0_sel:WORD_1
	v_pk_fma_f32 v[230:231], v[236:237], v[216:217], v[230:231]
	v_cvt_pk_f32_fp8_e32 v[236:237], v57
	v_pk_fma_f32 v[230:231], v[232:233], v[202:203], v[230:231]
	v_cvt_pk_f32_fp8_sdwa v[232:233], v58 src0_sel:WORD_1
	v_pk_fma_f32 v[230:231], v[234:235], v[204:205], v[230:231]
	v_cvt_pk_f32_fp8_e32 v[234:235], v59
	v_pk_fma_f32 v[230:231], v[236:237], v[206:207], v[230:231]
	v_cvt_pk_f32_fp8_sdwa v[236:237], v59 src0_sel:WORD_1
	v_pk_fma_f32 v[230:231], v[238:239], v[208:209], v[230:231]
	v_cvt_pk_f32_fp8_sdwa v[238:239], v61 src0_sel:WORD_1
	v_add_f32_e32 v240, v230, v231
	v_cvt_pk_f32_fp8_e32 v[230:231], v58
	v_pk_fma_f32 v[230:231], v[230:231], v[210:211], 0 op_sel_hi:[1,1,0]
	s_nop 0
	v_pk_fma_f32 v[230:231], v[232:233], v[212:213], v[230:231]
	v_cvt_pk_f32_fp8_e32 v[232:233], v60
	v_pk_fma_f32 v[230:231], v[234:235], v[214:215], v[230:231]
	v_cvt_pk_f32_fp8_sdwa v[234:235], v60 src0_sel:WORD_1
	v_pk_fma_f32 v[230:231], v[236:237], v[216:217], v[230:231]
	v_cvt_pk_f32_fp8_e32 v[236:237], v61
	v_pk_fma_f32 v[230:231], v[232:233], v[202:203], v[230:231]
	v_cvt_pk_f32_fp8_sdwa v[232:233], v62 src0_sel:WORD_1
	v_pk_fma_f32 v[230:231], v[234:235], v[204:205], v[230:231]
	v_cvt_pk_f32_fp8_e32 v[234:235], v63
	v_pk_fma_f32 v[230:231], v[236:237], v[206:207], v[230:231]
	v_cvt_pk_f32_fp8_sdwa v[236:237], v63 src0_sel:WORD_1
	v_pk_fma_f32 v[230:231], v[238:239], v[208:209], v[230:231]
	s_nop 0
	v_add_f32_e32 v238, v230, v231
	v_cvt_pk_f32_fp8_e32 v[230:231], v62
	v_pk_fma_f32 v[210:211], v[230:231], v[210:211], 0 op_sel_hi:[1,1,0]
	s_nop 0
	v_pk_fma_f32 v[210:211], v[232:233], v[212:213], v[210:211]
	v_cvt_pk_f32_fp8_e32 v[212:213], v64
	v_pk_fma_f32 v[210:211], v[234:235], v[214:215], v[210:211]
	v_cvt_pk_f32_fp8_sdwa v[214:215], v64 src0_sel:WORD_1
	v_pk_fma_f32 v[210:211], v[236:237], v[216:217], v[210:211]
	v_cvt_pk_f32_fp8_e32 v[216:217], v65
	v_cvt_pk_f32_fp8_sdwa v[230:231], v65 src0_sel:WORD_1
	v_pk_fma_f32 v[202:203], v[212:213], v[202:203], v[210:211]
	s_nop 0
	v_pk_fma_f32 v[202:203], v[214:215], v[204:205], v[202:203]
	v_cndmask_b32_e64 v204, v171, v187, s[8:9]
	v_pk_fma_f32 v[202:203], v[216:217], v[206:207], v[202:203]
	v_cndmask_b32_e64 v171, v187, v171, s[8:9]
	v_pk_fma_f32 v[202:203], v[230:231], v[208:209], v[202:203]
	v_cndmask_b32_e64 v187, v177, v240, s[8:9]
	v_add_f32_e32 v202, v202, v203
	v_cndmask_b32_e64 v203, v167, v183, s[8:9]
	v_cndmask_b32_e64 v167, v183, v167, s[8:9]
	ds_bpermute_b32 v183, v157, v203
	v_cndmask_b32_e64 v203, v169, v185, s[8:9]
	v_cndmask_b32_e64 v169, v185, v169, s[8:9]
	v_cndmask_b32_e64 v185, v175, v229, s[8:9]
	ds_bpermute_b32 v185, v157, v185
	s_waitcnt lgkmcnt(1)
; DI void dn2_math(const u32x4 (&W)[16], u32x4 x0, u32x4 x1, float* __restrict__ parow, int lane) {
;     ...
;   const bool b2 = lane & 4, b1 = lane & 2, b0 = lane & 1;
;   float q8[8];
; #pragma unroll
;   for (int i = 0; i < 8; ++i) { float snd = b2 ? pv[i] : pv[i + 8]; float kp = b2 ? pv[i + 8] : pv[i]; q8[i] = kp + __shfl_xor(snd, 4); }
;   float q4[4];
; #pragma unroll
;   for (int i = 0; i < 4; ++i) { float snd = b1 ? q8[i] : q8[i + 4]; float kp = b1 ? q8[i + 4] : q8[i]; q4[i] = kp + __shfl_xor(snd, 2); }
;   float r2[2];
; #pragma unroll
;   for (int i = 0; i < 2; ++i) { float snd = b0 ? q4[i] : q4[i + 2]; float kp = b0 ? q4[i + 2] : q4[i]; r2[i] = kp + __shfl_xor(snd, 1); }
;   const int j0 = (b0 ? 2 : 0) + (b1 ? 4 : 0) + (b2 ? 8 : 0);
;   const int grp = lane >> 3;
;   parow[8 * j0 + grp] = r2[0];
;   parow[8 * (j0 + 1) + grp] = r2[1];
; }
; DI void peer_down2_phase(const Params& p, unsigned char* smem, int layer, const bf16* __restrict__ x1b, u32* ctr) {
;     ...
;         if (tl + 2 < 16) {
;           dn2_issue(WA, pl + (tl + 2) * 128, wbase, grp);
;           xa0 = *(const u32x4*)(xb0 + (size_t)(tl + 2) * 1024); xa1 = *(const u32x4*)(xb0 + (size_t)(tl + 2) * 1024 + 8);
;         }
	v_add_f32_e32 v167, v167, v183
	v_cndmask_b32_e64 v183, v173, v189, s[8:9]
	ds_bpermute_b32 v183, v157, v183
	v_cndmask_b32_e64 v173, v189, v173, s[8:9]
	v_cndmask_b32_e64 v175, v229, v175, s[8:9]
	ds_bpermute_b32 v203, v157, v203
	ds_bpermute_b32 v204, v157, v204
	s_waitcnt lgkmcnt(2)
	v_add_f32_e32 v173, v173, v183
	v_cndmask_b32_e64 v183, v179, v238, s[8:9]
	ds_bpermute_b32 v187, v157, v187
	v_add_f32_e32 v175, v175, v185
	ds_bpermute_b32 v183, v157, v183
	v_cndmask_b32_e64 v185, v181, v202, s[8:9]
	ds_bpermute_b32 v185, v157, v185
	v_cndmask_b32_e64 v177, v240, v177, s[8:9]
	v_cndmask_b32_e64 v179, v238, v179, s[8:9]
	s_waitcnt lgkmcnt(4)
	v_add_f32_e32 v169, v169, v203
	s_waitcnt lgkmcnt(3)
	v_add_f32_e32 v171, v171, v204
	s_waitcnt lgkmcnt(2)
	v_add_f32_e32 v177, v177, v187
	s_waitcnt lgkmcnt(1)
	v_add_f32_e32 v179, v179, v183
	v_cndmask_b32_e64 v181, v202, v181, s[8:9]
	v_cndmask_b32_e64 v187, v167, v175, s[10:11]
	s_waitcnt lgkmcnt(0)
	v_add_f32_e32 v181, v181, v185
	v_cndmask_b32_e64 v167, v175, v167, s[10:11]
	v_cndmask_b32_e64 v175, v169, v177, s[10:11]
	v_cndmask_b32_e64 v169, v177, v169, s[10:11]
	v_cndmask_b32_e64 v177, v171, v179, s[10:11]
	ds_bpermute_b32 v187, v159, v187
	ds_bpermute_b32 v177, v159, v177
	v_cndmask_b32_e64 v183, v173, v181, s[10:11]
	ds_bpermute_b32 v175, v159, v175
	ds_bpermute_b32 v183, v159, v183
	v_cndmask_b32_e64 v171, v179, v171, s[10:11]
	s_waitcnt lgkmcnt(3)
	v_add_f32_e32 v167, v167, v187
	s_waitcnt lgkmcnt(2)
	v_add_f32_e32 v171, v171, v177
	v_cndmask_b32_e64 v173, v181, v173, s[10:11]
	s_waitcnt lgkmcnt(1)
	v_add_f32_e32 v169, v169, v175
	s_waitcnt lgkmcnt(0)
	v_add_f32_e32 v173, v173, v183
	v_cndmask_b32_e64 v175, v167, v171, s[12:13]
	ds_bpermute_b32 v175, v163, v175
	v_cndmask_b32_e64 v177, v169, v173, s[12:13]
	ds_bpermute_b32 v177, v163, v177
	v_cndmask_b32_e64 v167, v171, v167, s[12:13]
	v_cndmask_b32_e64 v169, v173, v169, s[12:13]
	s_waitcnt lgkmcnt(1)
	v_add_f32_e32 v167, v167, v175
	s_waitcnt lgkmcnt(0)
	v_add_f32_e32 v169, v169, v177
	global_store_dword v[200:201], v167, off offset:-512
	global_store_dword v[200:201], v169, off offset:-480
	s_cmp_gt_u32 s40, 13
	s_cselect_b64 s[28:29], -1, 0
	s_and_b64 vcc, exec, s[28:29]
	s_cbranch_vccnz .LBB0_1516
	ds_read2_b32 v[2:3], v165 offset0:128 offset1:136
	ds_read2_b32 v[10:11], v165 offset0:144 offset1:152
	ds_read2_b32 v[18:19], v165 offset0:160 offset1:168
	ds_read2_b32 v[26:27], v165 offset0:176 offset1:184
	ds_read2_b32 v[34:35], v165 offset0:192 offset1:200
	ds_read2_b32 v[42:43], v165 offset0:208 offset1:216
	ds_read2_b32 v[50:51], v165 offset0:224 offset1:232
	ds_read2_b32 v[58:59], v165 offset0:240 offset1:248
	s_waitcnt lgkmcnt(7)
	v_lshl_add_u32 v6, v3, 10, v250
	v_lshl_add_u32 v2, v2, 10, v250
	global_load_dwordx4 v[2:5], v2, s[98:99]
	global_load_dwordx4 v[6:9], v6, s[98:99]
	s_waitcnt lgkmcnt(6)
	v_lshl_add_u32 v14, v11, 10, v250
	v_lshl_add_u32 v10, v10, 10, v250
	global_load_dwordx4 v[10:13], v10, s[98:99]
	global_load_dwordx4 v[14:17], v14, s[98:99]
	s_waitcnt lgkmcnt(5)
	v_lshl_add_u32 v22, v19, 10, v250
	v_lshl_add_u32 v18, v18, 10, v250
	global_load_dwordx4 v[18:21], v18, s[98:99]
	global_load_dwordx4 v[22:25], v22, s[98:99]
	s_waitcnt lgkmcnt(4)
	v_lshl_add_u32 v30, v27, 10, v250
	v_lshl_add_u32 v26, v26, 10, v250
	global_load_dwordx4 v[26:29], v26, s[98:99]
	global_load_dwordx4 v[30:33], v30, s[98:99]
	s_waitcnt lgkmcnt(3)
	v_lshl_add_u32 v38, v35, 10, v250
	v_lshl_add_u32 v34, v34, 10, v250
	global_load_dwordx4 v[34:37], v34, s[98:99]
	global_load_dwordx4 v[38:41], v38, s[98:99]
	s_waitcnt lgkmcnt(2)
	v_lshl_add_u32 v46, v43, 10, v250
	v_lshl_add_u32 v42, v42, 10, v250
	global_load_dwordx4 v[42:45], v42, s[98:99]
	global_load_dwordx4 v[46:49], v46, s[98:99]
	s_waitcnt lgkmcnt(1)
	v_lshl_add_u32 v54, v51, 10, v250
	v_lshl_add_u32 v50, v50, 10, v250
	global_load_dwordx4 v[50:53], v50, s[98:99]
	global_load_dwordx4 v[54:57], v54, s[98:99]
	s_waitcnt lgkmcnt(0)
	v_lshl_add_u32 v62, v59, 10, v250
	v_lshl_add_u32 v58, v58, 10, v250
	global_load_dwordx4 v[58:61], v58, s[98:99]
	global_load_dwordx4 v[62:65], v62, s[98:99]
	s_nop 0
	global_load_dwordx4 v[66:69], v[198:199], off offset:16
	global_load_dwordx4 v[70:73], v[198:199], off
	s_branch .LBB0_1516
